# one workgroup barrier per MFMA block: leading half syncs after its MFMAs, trailing half after its loads; trailing half's MFMA block at priority 2
# baseline (speedup 1.0000x reference)
.LBB0_160:
	s_or_b64 exec, exec, s[0:1]
	v_readlane_b32 s26, v241, 6
	s_cmp_eq_u32 s19, 0
	v_mov_b32_e32 v14, v156
	v_readlane_b32 s27, v241, 7
	s_cselect_b64 s[0:1], -1, 0
	s_waitcnt lgkmcnt(0)
	s_barrier
	s_and_b64 vcc, exec, s[26:27]
	v_readfirstlane_b32 s28, v14
	s_cbranch_vccz .LBB0_176
	v_lshlrev_b32_e32 v1, 4, v14
	v_add_u32_e32 v0, 0x2000, v1
	v_ashrrev_i32_e32 v3, 31, v0
	v_lshrrev_b32_e32 v3, 22, v3
	v_add_u32_e32 v3, v0, v3
	v_ashrrev_i32_e32 v8, 10, v3
	v_mul_i32_i24_e32 v3, 0x400, v8
	v_sub_u32_e32 v0, v0, v3
	v_lshrrev_b32_e32 v3, 4, v0
	v_bitop3_b32 v0, v3, v0, 32 bitop3:0x6c
	s_ashr_i32 s29, s28, 6
	v_ashrrev_i32_e32 v3, 31, v0
	s_ashr_i32 s36, s28, 8
	s_lshl_b32 s19, s29, 10
	v_lshrrev_b32_e32 v3, 26, v3
	s_and_b64 s[26:27], s[0:1], exec
	v_add_u32_e32 v3, v0, v3
	v_lshlrev_b32_e32 v4, 3, v8
	s_cselect_b32 s26, 0, 0x5800000
	v_ashrrev_i32_e32 v9, 6, v3
	v_and_b32_e32 v4, -16, v4
	s_add_u32 s33, s88, s26
	v_readlane_b32 s26, v240, 13
	v_add_u32_e32 v4, v9, v4
	s_addc_u32 s56, s26, 0
	v_and_b32_e32 v5, 3, v9
	s_mov_b32 s26, 0x1ffffe0
	v_lshrrev_b32_e32 v6, 2, v4
	v_lshlrev_b32_e32 v7, 1, v4
	v_and_b32_e32 v3, 0xc0, v3
	v_and_or_b32 v5, v4, s26, v5
	v_and_b32_e32 v6, 4, v6
	v_and_b32_e32 v7, 24, v7
	v_sub_u32_e32 v0, v0, v3
	v_or3_b32 v5, v5, v6, v7
	v_lshlrev_b32_e32 v6, 5, v8
	v_ashrrev_i16_sdwa v0, v220, sext(v0) dst_sel:DWORD dst_unused:UNUSED_PAD src0_sel:DWORD src1_sel:BYTE_0
	v_and_b32_e32 v6, 32, v6
	v_bfe_i32 v10, v0, 0, 16
	v_add_lshl_u32 v3, v6, v10, 1
	v_lshl_add_u32 v0, v5, 7, v3
	v_lshl_add_u32 v132, v4, 12, v3
	v_bfe_i32 v3, v14, 27, 1
	v_lshrrev_b32_e32 v3, 22, v3
	v_add_u32_e32 v3, v1, v3
	v_and_b32_e32 v3, 0xfffffc00, v3
	v_sub_u32_e32 v1, v1, v3
	v_lshrrev_b32_e32 v3, 4, v1
	v_ashrrev_i32_e32 v4, 31, v14
	v_bitop3_b32 v1, v3, v1, 32 bitop3:0x6c
	v_lshrrev_b32_e32 v4, 26, v4
	v_ashrrev_i32_e32 v3, 31, v1
	v_add_u32_e32 v4, v14, v4
	v_lshrrev_b32_e32 v3, 26, v3
	v_ashrrev_i32_e32 v12, 6, v4
	v_add_u32_e32 v3, v1, v3
	v_lshlrev_b32_e32 v4, 3, v12
	v_ashrrev_i32_e32 v11, 6, v3
	v_and_b32_e32 v4, -16, v4
	v_add_u32_e32 v4, v11, v4
	v_and_b32_e32 v5, 3, v11
	v_lshrrev_b32_e32 v6, 2, v4
	v_lshlrev_b32_e32 v7, 1, v4
	v_and_b32_e32 v3, 0xc0, v3
	v_and_or_b32 v5, v4, s26, v5
	v_and_b32_e32 v6, 4, v6
	v_and_b32_e32 v7, 24, v7
	v_sub_u32_e32 v1, v1, v3
	v_or3_b32 v5, v5, v6, v7
	v_lshlrev_b32_e32 v6, 5, v12
	v_ashrrev_i16_sdwa v1, v220, sext(v1) dst_sel:DWORD dst_unused:UNUSED_PAD src0_sel:DWORD src1_sel:BYTE_0
	v_readlane_b32 s26, v241, 51
	v_and_b32_e32 v6, 32, v6
	v_bfe_i32 v13, v1, 0, 16
	v_readlane_b32 s27, v241, 52
	s_add_u32 s34, s33, s26
	v_add_lshl_u32 v1, v6, v13, 1
	s_addc_u32 s35, s56, s27
	s_add_i32 s57, s19, 0
	v_lshl_add_u32 v134, v5, 7, v1
	s_add_i32 m0, s57, 0x10000
	v_lshl_add_u32 v136, v4, 12, v1
	global_load_lds_dwordx4 v134, s[34:35]
	s_add_i32 m0, s57, 0x12000
	s_add_u32 s26, s34, 0x4000
	global_load_lds_dwordx4 v0, s[34:35]
	s_addc_u32 s27, s35, 0
	s_add_i32 m0, s57, 0x14000
	v_mov_b32_e32 v137, v2
	global_load_lds_dwordx4 v134, s[26:27]
	s_add_i32 m0, s57, 0x16000
	v_mov_b32_e32 v133, v2
	global_load_lds_dwordx4 v0, s[26:27]
	v_readlane_b32 s26, v241, 62
	v_readlane_b32 s27, v241, 63
	s_add_u32 s50, s20, s26
	s_addc_u32 s51, s21, s27
	s_add_i32 s58, s57, 0x2000
	s_mov_b32 m0, s57
	s_add_u32 s26, s50, 0x80000
	global_load_lds_dwordx4 v136, s[50:51]
	s_mov_b32 m0, s58
	s_addc_u32 s27, s51, 0
	s_add_i32 s59, s57, 0x4000
	global_load_lds_dwordx4 v132, s[50:51]
	s_mov_b32 m0, s59
	s_add_i32 s60, s57, 0x6000
	global_load_lds_dwordx4 v136, s[26:27]
	s_mov_b32 m0, s60
	s_cmp_eq_u32 s36, 1
	global_load_lds_dwordx4 v132, s[26:27]
	v_lshl_add_u64 v[4:5], s[50:51], 0, v[136:137]
	s_cselect_b64 s[26:27], -1, 0
	s_cmp_lg_u32 s36, 1
	v_lshl_add_u64 v[6:7], s[50:51], 0, v[132:133]
	s_cbranch_scc1 .LBB0_163
	s_nop 0

.LBB0_168:
	s_ashr_i32 s43, s42, 31
	s_lshl_b64 s[36:37], s[42:43], 20
	s_add_u32 s44, s20, s36
	s_addc_u32 s45, s21, s37
	s_and_b64 s[36:37], s[38:39], exec
	s_cselect_b32 s36, s45, s51
	s_cselect_b32 s37, s44, s50
	s_ashr_i32 s41, s40, 31
	s_lshl_b64 s[46:47], s[40:41], 15
	s_add_u32 s46, s33, s46
	s_addc_u32 s47, s56, s47
	s_and_b64 s[54:55], s[38:39], exec
	s_cselect_b32 s41, s47, s35
	s_cselect_b32 s43, s46, s34
	s_add_u32 s71, s34, 0x2c0000
	s_addc_u32 s76, s35, 0
	s_add_u32 s50, s50, 0x80080
	v_mov_b32_e32 v4, 0
	s_addc_u32 s51, s51, 0
	s_mov_b32 s77, -2
	v_mov_b32_e32 v5, v4
	v_mov_b32_e32 v6, v4
	v_mov_b32_e32 v7, v4
	v_mov_b32_e32 v8, v4
	v_mov_b32_e32 v9, v4
	v_mov_b32_e32 v10, v4
	v_mov_b32_e32 v11, v4
	v_mov_b32_e32 v20, v4
	v_mov_b32_e32 v21, v4
	v_mov_b32_e32 v22, v4
	v_mov_b32_e32 v23, v4
	v_mov_b32_e32 v24, v4
	v_mov_b32_e32 v25, v4
	v_mov_b32_e32 v26, v4
	v_mov_b32_e32 v27, v4
	v_mov_b32_e32 v36, v4
	v_mov_b32_e32 v37, v4
	v_mov_b32_e32 v38, v4
	v_mov_b32_e32 v39, v4
	v_mov_b32_e32 v40, v4
	v_mov_b32_e32 v41, v4
	v_mov_b32_e32 v42, v4
	v_mov_b32_e32 v43, v4
	v_mov_b32_e32 v52, v4
	v_mov_b32_e32 v53, v4
	v_mov_b32_e32 v54, v4
	v_mov_b32_e32 v55, v4
	v_mov_b32_e32 v56, v4
	v_mov_b32_e32 v57, v4
	v_mov_b32_e32 v58, v4
	v_mov_b32_e32 v59, v4
	v_mov_b32_e32 v12, v4
	v_mov_b32_e32 v13, v4
	v_mov_b32_e32 v14, v4
	v_mov_b32_e32 v15, v4
	v_mov_b32_e32 v16, v4
	v_mov_b32_e32 v17, v4
	v_mov_b32_e32 v18, v4
	v_mov_b32_e32 v19, v4
	v_mov_b32_e32 v28, v4
	v_mov_b32_e32 v29, v4
	v_mov_b32_e32 v30, v4
	v_mov_b32_e32 v31, v4
	v_mov_b32_e32 v32, v4
	v_mov_b32_e32 v33, v4
	v_mov_b32_e32 v34, v4
	v_mov_b32_e32 v35, v4
	v_mov_b32_e32 v44, v4
	v_mov_b32_e32 v45, v4
	v_mov_b32_e32 v46, v4
	v_mov_b32_e32 v47, v4
	v_mov_b32_e32 v48, v4
	v_mov_b32_e32 v49, v4
	v_mov_b32_e32 v50, v4
	v_mov_b32_e32 v51, v4
	v_mov_b32_e32 v60, v4
	v_mov_b32_e32 v61, v4
	v_mov_b32_e32 v62, v4
	v_mov_b32_e32 v63, v4
	v_mov_b32_e32 v64, v4
	v_mov_b32_e32 v65, v4
	v_mov_b32_e32 v66, v4
	v_mov_b32_e32 v67, v4
	v_mov_b32_e32 v68, v4
	v_mov_b32_e32 v69, v4
	v_mov_b32_e32 v70, v4
	v_mov_b32_e32 v71, v4
	v_mov_b32_e32 v72, v4
	v_mov_b32_e32 v73, v4
	v_mov_b32_e32 v74, v4
	v_mov_b32_e32 v75, v4
	v_mov_b32_e32 v84, v4
	v_mov_b32_e32 v85, v4
	v_mov_b32_e32 v86, v4
	v_mov_b32_e32 v87, v4
	v_mov_b32_e32 v88, v4
	v_mov_b32_e32 v89, v4
	v_mov_b32_e32 v90, v4
	v_mov_b32_e32 v91, v4
	v_mov_b32_e32 v100, v4
	v_mov_b32_e32 v101, v4
	v_mov_b32_e32 v102, v4
	v_mov_b32_e32 v103, v4
	v_mov_b32_e32 v104, v4
	v_mov_b32_e32 v105, v4
	v_mov_b32_e32 v106, v4
	v_mov_b32_e32 v107, v4
	v_mov_b32_e32 v116, v4
	v_mov_b32_e32 v117, v4
	v_mov_b32_e32 v118, v4
	v_mov_b32_e32 v119, v4
	v_mov_b32_e32 v120, v4
	v_mov_b32_e32 v121, v4
	v_mov_b32_e32 v122, v4
	v_mov_b32_e32 v123, v4
	v_mov_b32_e32 v76, v4
	v_mov_b32_e32 v77, v4
	v_mov_b32_e32 v78, v4
	v_mov_b32_e32 v79, v4
	v_mov_b32_e32 v80, v4
	v_mov_b32_e32 v81, v4
	v_mov_b32_e32 v82, v4
	v_mov_b32_e32 v83, v4
	v_mov_b32_e32 v92, v4
	v_mov_b32_e32 v93, v4
	v_mov_b32_e32 v94, v4
	v_mov_b32_e32 v95, v4
	v_mov_b32_e32 v96, v4
	v_mov_b32_e32 v97, v4
	v_mov_b32_e32 v98, v4
	v_mov_b32_e32 v99, v4
	v_mov_b32_e32 v108, v4
	v_mov_b32_e32 v109, v4
	v_mov_b32_e32 v110, v4
	v_mov_b32_e32 v111, v4
	v_mov_b32_e32 v112, v4
	v_mov_b32_e32 v113, v4
	v_mov_b32_e32 v114, v4
	v_mov_b32_e32 v115, v4
	v_mov_b32_e32 v124, v4
	v_mov_b32_e32 v125, v4
	v_mov_b32_e32 v126, v4
	v_mov_b32_e32 v127, v4
	v_mov_b32_e32 v128, v4
	v_mov_b32_e32 v129, v4
	v_mov_b32_e32 v130, v4
	v_mov_b32_e32 v131, v4
	v_readfirstlane_b32 s101, v156
	s_bfe_u32 s101, s101, 0x10008
.LBB0_169:
	s_add_u32 s34, s50, 0xfff80080
	s_addc_u32 s35, s51, -1
	s_add_i32 s52, 0, 0x10000
	s_cmp_eq_u32 s77, 28
	s_cselect_b32 s55, s36, s35
	s_cselect_b32 s54, s37, s34
	v_add_u32_e32 v145, s52, v142
	s_cselect_b32 s35, s41, s76
	s_cselect_b32 s34, s43, s71
	s_add_i32 s53, 0, 0x14000
	ds_read_b128 v[146:149], v145
	ds_read_b128 v[150:153], v145 offset:1024
	ds_read_b128 v[172:175], v145 offset:2048
	ds_read_b128 v[176:179], v145 offset:3072
	v_add_u32_e32 v145, s53, v142
	ds_read_b128 v[180:183], v145
	ds_read_b128 v[184:187], v145 offset:1024
	ds_read_b128 v[188:191], v145 offset:2048
	ds_read_b128 v[192:195], v145 offset:3072
	v_lshl_add_u64 v[154:155], s[50:51], 0, v[138:139]
	s_add_i32 m0, s57, 0xc000
	ds_read_b128 v[196:199], v144
	ds_read_b128 v[200:203], v144 offset:1024
	ds_read_b128 v[204:207], v144 offset:2048
	ds_read_b128 v[208:211], v144 offset:3072
	ds_read_b128 v[212:215], v144 offset:4096
	ds_read_b128 v[216:219], v144 offset:5120
	ds_read_b128 v[228:231], v144 offset:6144
	ds_read_b128 v[232:235], v144 offset:7168
	global_load_lds_dwordx4 v[154:155], off
	v_lshl_add_u64 v[154:155], s[50:51], 0, v[140:141]
	s_add_i32 m0, s57, 0xe000
	s_nop 0
	global_load_lds_dwordx4 v[154:155], off
	s_waitcnt vmcnt(8)
	s_waitcnt lgkmcnt(0)
	s_cmp_eq_u32 s101, 0
	s_cbranch_scc1 .LnbA_1
	s_barrier
	s_setprio 2
	s_branch .Lnb_1
.LnbA_1:
	s_setprio 1
.Lnb_1:
	v_mfma_f32_16x16x32_bf16 v[128:131], v[146:149], v[196:199], v[128:131]
	v_mfma_f32_16x16x32_bf16 v[128:131], v[150:153], v[200:203], v[128:131]
	v_mfma_f32_16x16x32_bf16 v[124:127], v[172:175], v[196:199], v[124:127]
	v_mfma_f32_16x16x32_bf16 v[124:127], v[176:179], v[200:203], v[124:127]
	v_mfma_f32_16x16x32_bf16 v[108:111], v[172:175], v[204:207], v[108:111]
	v_mfma_f32_16x16x32_bf16 v[108:111], v[176:179], v[208:211], v[108:111]
	v_mfma_f32_16x16x32_bf16 v[112:115], v[146:149], v[204:207], v[112:115]
	v_mfma_f32_16x16x32_bf16 v[112:115], v[150:153], v[208:211], v[112:115]
	v_mfma_f32_16x16x32_bf16 v[96:99], v[146:149], v[212:215], v[96:99]
	v_mfma_f32_16x16x32_bf16 v[96:99], v[150:153], v[216:219], v[96:99]
	v_mfma_f32_16x16x32_bf16 v[92:95], v[172:175], v[212:215], v[92:95]
	v_mfma_f32_16x16x32_bf16 v[92:95], v[176:179], v[216:219], v[92:95]
	v_mfma_f32_16x16x32_bf16 v[76:79], v[172:175], v[228:231], v[76:79]
	v_mfma_f32_16x16x32_bf16 v[76:79], v[176:179], v[232:235], v[76:79]
	v_mfma_f32_16x16x32_bf16 v[80:83], v[146:149], v[228:231], v[80:83]
	v_mfma_f32_16x16x32_bf16 v[80:83], v[150:153], v[232:235], v[80:83]
	v_mfma_f32_16x16x32_bf16 v[120:123], v[180:183], v[196:199], v[120:123]
	v_mfma_f32_16x16x32_bf16 v[120:123], v[184:187], v[200:203], v[120:123]
	v_mfma_f32_16x16x32_bf16 v[116:119], v[188:191], v[196:199], v[116:119]
	v_mfma_f32_16x16x32_bf16 v[116:119], v[192:195], v[200:203], v[116:119]
	v_mfma_f32_16x16x32_bf16 v[100:103], v[188:191], v[204:207], v[100:103]
	v_mfma_f32_16x16x32_bf16 v[100:103], v[192:195], v[208:211], v[100:103]
	v_mfma_f32_16x16x32_bf16 v[104:107], v[180:183], v[204:207], v[104:107]
	v_mfma_f32_16x16x32_bf16 v[104:107], v[184:187], v[208:211], v[104:107]
	v_mfma_f32_16x16x32_bf16 v[88:91], v[180:183], v[212:215], v[88:91]
	v_mfma_f32_16x16x32_bf16 v[88:91], v[184:187], v[216:219], v[88:91]
	v_mfma_f32_16x16x32_bf16 v[84:87], v[188:191], v[212:215], v[84:87]
	v_mfma_f32_16x16x32_bf16 v[84:87], v[192:195], v[216:219], v[84:87]
	v_mfma_f32_16x16x32_bf16 v[68:71], v[188:191], v[228:231], v[68:71]
	v_mfma_f32_16x16x32_bf16 v[68:71], v[192:195], v[232:235], v[68:71]
	v_mfma_f32_16x16x32_bf16 v[72:75], v[180:183], v[228:231], v[72:75]
	v_mfma_f32_16x16x32_bf16 v[72:75], v[184:187], v[232:235], v[72:75]
	s_setprio 0
	s_cmp_lg_u32 s101, 0
	s_cbranch_scc1 .Lnb_2
	s_barrier
.Lnb_2:
	s_add_i32 s52, s52, s19
	v_lshl_add_u64 v[154:155], s[34:35], 0, v[134:135]
	s_mov_b32 m0, s52
	ds_read_b128 v[196:199], v144 offset:16384
	ds_read_b128 v[200:203], v144 offset:17408
	ds_read_b128 v[204:207], v144 offset:18432
	ds_read_b128 v[208:211], v144 offset:19456
	ds_read_b128 v[212:215], v144 offset:20480
	ds_read_b128 v[216:219], v144 offset:21504
	ds_read_b128 v[228:231], v144 offset:22528
	ds_read_b128 v[232:235], v144 offset:23552
	global_load_lds_dwordx4 v[154:155], off
	s_add_i32 m0, s52, 0x2000
	s_add_u32 s96, s34, 0x4000
	v_lshl_add_u64 v[154:155], s[34:35], 0, v[0:1]
	s_addc_u32 s97, s35, 0
	s_add_i32 s52, s53, s19
	global_load_lds_dwordx4 v[154:155], off
	v_lshl_add_u64 v[154:155], s[96:97], 0, v[134:135]
	s_mov_b32 m0, s52
	v_lshl_add_u64 v[236:237], s[54:55], 0, v[132:133]
	global_load_lds_dwordx4 v[154:155], off
	v_lshl_add_u64 v[154:155], s[96:97], 0, v[0:1]
	s_add_i32 m0, s52, 0x2000
	s_nop 0
	global_load_lds_dwordx4 v[154:155], off
	v_lshl_add_u64 v[154:155], s[54:55], 0, v[136:137]
	s_mov_b32 m0, s57
	s_nop 0
	global_load_lds_dwordx4 v[154:155], off
	s_mov_b32 m0, s58
	s_nop 0
	global_load_lds_dwordx4 v[236:237], off
	s_waitcnt vmcnt(8)
	s_waitcnt lgkmcnt(0)
	s_cmp_eq_u32 s101, 0
	s_cbranch_scc1 .LnbA_2
	s_barrier
	s_setprio 2
	s_branch .Lnb_3

.Lnb_3:
	v_mfma_f32_16x16x32_bf16 v[64:67], v[146:149], v[196:199], v[64:67]
	v_mfma_f32_16x16x32_bf16 v[64:67], v[150:153], v[200:203], v[64:67]
	v_mfma_f32_16x16x32_bf16 v[60:63], v[172:175], v[196:199], v[60:63]
	v_mfma_f32_16x16x32_bf16 v[60:63], v[176:179], v[200:203], v[60:63]
	v_mfma_f32_16x16x32_bf16 v[44:47], v[172:175], v[204:207], v[44:47]
	v_mfma_f32_16x16x32_bf16 v[44:47], v[176:179], v[208:211], v[44:47]
	v_mfma_f32_16x16x32_bf16 v[48:51], v[146:149], v[204:207], v[48:51]
	v_mfma_f32_16x16x32_bf16 v[48:51], v[150:153], v[208:211], v[48:51]
	v_mfma_f32_16x16x32_bf16 v[32:35], v[146:149], v[212:215], v[32:35]
	v_mfma_f32_16x16x32_bf16 v[32:35], v[150:153], v[216:219], v[32:35]
	v_mfma_f32_16x16x32_bf16 v[28:31], v[172:175], v[212:215], v[28:31]
	v_mfma_f32_16x16x32_bf16 v[28:31], v[176:179], v[216:219], v[28:31]
	v_mfma_f32_16x16x32_bf16 v[12:15], v[172:175], v[228:231], v[12:15]
	v_mfma_f32_16x16x32_bf16 v[12:15], v[176:179], v[232:235], v[12:15]
	v_mfma_f32_16x16x32_bf16 v[16:19], v[146:149], v[228:231], v[16:19]
	v_mfma_f32_16x16x32_bf16 v[16:19], v[150:153], v[232:235], v[16:19]
	v_mfma_f32_16x16x32_bf16 v[56:59], v[180:183], v[196:199], v[56:59]
	v_mfma_f32_16x16x32_bf16 v[56:59], v[184:187], v[200:203], v[56:59]
	v_mfma_f32_16x16x32_bf16 v[52:55], v[188:191], v[196:199], v[52:55]
	v_mfma_f32_16x16x32_bf16 v[52:55], v[192:195], v[200:203], v[52:55]
	v_mfma_f32_16x16x32_bf16 v[36:39], v[188:191], v[204:207], v[36:39]
	v_mfma_f32_16x16x32_bf16 v[36:39], v[192:195], v[208:211], v[36:39]
	v_mfma_f32_16x16x32_bf16 v[40:43], v[180:183], v[204:207], v[40:43]
	v_mfma_f32_16x16x32_bf16 v[40:43], v[184:187], v[208:211], v[40:43]
	v_mfma_f32_16x16x32_bf16 v[24:27], v[180:183], v[212:215], v[24:27]
	v_mfma_f32_16x16x32_bf16 v[24:27], v[184:187], v[216:219], v[24:27]
	v_mfma_f32_16x16x32_bf16 v[20:23], v[188:191], v[212:215], v[20:23]
	v_mfma_f32_16x16x32_bf16 v[20:23], v[192:195], v[216:219], v[20:23]
	v_mfma_f32_16x16x32_bf16 v[4:7], v[188:191], v[228:231], v[4:7]
	v_mfma_f32_16x16x32_bf16 v[4:7], v[192:195], v[232:235], v[4:7]
	v_mfma_f32_16x16x32_bf16 v[8:11], v[180:183], v[228:231], v[8:11]
	v_mfma_f32_16x16x32_bf16 v[8:11], v[184:187], v[232:235], v[8:11]
	s_setprio 0
	s_cmp_lg_u32 s101, 0
	s_cbranch_scc1 .Lnb_4
	s_barrier
.Lnb_4:
	s_add_i32 s52, 0, 0x18000
	v_add_u32_e32 v145, s52, v142
	s_add_i32 s53, 0, 0x1c000
	ds_read_b128 v[146:149], v145
	ds_read_b128 v[150:153], v145 offset:1024
	ds_read_b128 v[172:175], v145 offset:2048
	ds_read_b128 v[176:179], v145 offset:3072
	v_add_u32_e32 v145, s53, v142
	ds_read_b128 v[180:183], v145
	ds_read_b128 v[184:187], v145 offset:1024
	ds_read_b128 v[188:191], v145 offset:2048
	ds_read_b128 v[192:195], v145 offset:3072
	s_add_u32 s54, s54, 0x80000
	s_addc_u32 s55, s55, 0
	s_mov_b32 m0, s59
	v_lshl_add_u64 v[238:239], s[54:55], 0, v[136:137]
	ds_read_b128 v[196:199], v144 offset:32768
	ds_read_b128 v[200:203], v144 offset:33792
	ds_read_b128 v[204:207], v144 offset:34816
	ds_read_b128 v[208:211], v144 offset:35840
	ds_read_b128 v[212:215], v144 offset:36864
	ds_read_b128 v[216:219], v144 offset:37888
	ds_read_b128 v[228:231], v144 offset:38912
	ds_read_b128 v[232:235], v144 offset:39936
	global_load_lds_dwordx4 v[238:239], off
	v_lshl_add_u64 v[238:239], s[54:55], 0, v[132:133]
	s_mov_b32 m0, s60
	s_nop 0
	global_load_lds_dwordx4 v[238:239], off
	s_waitcnt vmcnt(8)
	s_waitcnt lgkmcnt(0)
	s_cmp_eq_u32 s101, 0
	s_cbranch_scc1 .LnbA_3
	s_barrier
	s_setprio 2
	s_branch .Lnb_5

.Lnb_6:
	s_add_u32 s54, s34, 0x160000
	s_addc_u32 s55, s35, 0
	s_add_i32 s52, s52, s19
	v_lshl_add_u64 v[238:239], s[54:55], 0, v[134:135]
	s_mov_b32 m0, s52
	ds_read_b128 v[196:199], v144 offset:49152
	ds_read_b128 v[200:203], v144 offset:50176
	ds_read_b128 v[204:207], v144 offset:51200
	ds_read_b128 v[208:211], v144 offset:52224
	ds_read_b128 v[212:215], v144 offset:53248
	ds_read_b128 v[216:219], v144 offset:54272
	ds_read_b128 v[228:231], v144 offset:55296
	ds_read_b128 v[232:235], v144 offset:56320
	global_load_lds_dwordx4 v[238:239], off
	s_add_i32 m0, s52, 0x2000
	s_add_u32 s34, s34, 0x164000
	v_lshl_add_u64 v[238:239], s[54:55], 0, v[0:1]
	s_addc_u32 s35, s35, 0
	s_add_i32 s52, s53, s19
	global_load_lds_dwordx4 v[238:239], off
	v_lshl_add_u64 v[238:239], s[34:35], 0, v[134:135]
	s_mov_b32 m0, s52
	v_lshl_add_u64 v[154:155], v[154:155], 0, s[14:15]
	global_load_lds_dwordx4 v[238:239], off
	v_lshl_add_u64 v[238:239], s[34:35], 0, v[0:1]
	s_add_i32 m0, s52, 0x2000
	s_nop 0
	global_load_lds_dwordx4 v[238:239], off
	s_mov_b32 m0, s61
	s_nop 0
	global_load_lds_dwordx4 v[154:155], off
	v_lshl_add_u64 v[154:155], v[236:237], 0, s[14:15]
	s_mov_b32 m0, s62
	s_nop 0
	global_load_lds_dwordx4 v[154:155], off
	s_waitcnt vmcnt(8)
	s_waitcnt lgkmcnt(0)
	s_cmp_eq_u32 s101, 0
	s_cbranch_scc1 .LnbA_4
	s_barrier
	s_setprio 2
	s_branch .Lnb_7

.Lnb_8:
	s_add_i32 s77, s77, 2
	s_add_u32 s71, s71, 0x2c0000
	s_addc_u32 s76, s76, 0
	s_add_u32 s50, s50, 0x100
	s_addc_u32 s51, s51, 0
	s_cmp_gt_u32 s77, 29
	s_cbranch_scc0 .LBB0_169
	s_and_b64 vcc, exec, s[28:29]
	s_nop 0
	s_barrier
.LBB0_172:
	v_lshl_add_u32 v153, s69, 8, v3
	v_and_b32_e32 v145, 0x7cf, v153
	v_lshl_add_u32 v147, v145, 2, s92
	v_bitop3_b32 v145, v153, s5, 16 bitop3:0xc8
	v_lshl_add_u32 v149, v145, 2, s92
	v_bitop3_b32 v145, v153, s8, 32 bitop3:0xc8
	v_lshl_add_u32 v150, v145, 2, s92
	v_bitop3_b32 v145, v153, s9, 48 bitop3:0xc8
	v_add_u32_e32 v176, 0x80, v153
	v_lshl_add_u32 v151, v145, 2, s92
	v_and_b32_e32 v145, 0x7cf, v176
	v_add_u32_e32 v148, 0x90, v153
	v_lshl_add_u32 v152, v145, 2, s92
	v_and_b32_e32 v145, 0x7df, v148
	v_add_u32_e32 v146, 0xa0, v153
	v_lshl_add_u32 v154, v145, 2, s92
	v_and_b32_e32 v145, 0x7ef, v146
	v_lshl_add_u32 v172, v145, 2, s92
	v_add_u32_e32 v145, 0xb0, v153
	v_and_b32_e32 v173, 0x7ff, v145
	v_lshl_add_u32 v173, v173, 2, s92
	ds_read_b32 v177, v147
	ds_read_b32 v178, v149
	ds_read_b32 v179, v150
	ds_read_b32 v180, v151
	ds_read_b32 v181, v152
	ds_read_b32 v182, v154
	ds_read_b32 v149, v172
	ds_read_b32 v147, v173
	s_waitcnt lgkmcnt(0)
	v_mul_f32_e32 v152, 0xbfb8aa3b, v177
	v_pk_mul_f32 v[172:173], v[128:129], v[152:153] op_sel_hi:[1,0]
	v_pk_mul_f32 v[122:123], v[130:131], v[122:123]
	v_pk_mul_f32 v[120:121], v[128:129], v[120:121]
	v_exp_f32_e32 v128, v172
	v_exp_f32_e32 v129, v173
	v_pk_mul_f32 v[130:131], v[130:131], v[152:153] op_sel_hi:[1,0]
	v_pk_mul_f32 v[172:173], v[124:125], v[152:153] op_sel_hi:[1,0]
	v_exp_f32_e32 v130, v130
	v_exp_f32_e32 v131, v131
	v_pk_mul_f32 v[118:119], v[126:127], v[118:119]
	v_pk_mul_f32 v[116:117], v[124:125], v[116:117]
	v_exp_f32_e32 v124, v172
	v_exp_f32_e32 v125, v173
	v_pk_mul_f32 v[126:127], v[126:127], v[152:153] op_sel_hi:[1,0]
	v_pk_add_f32 v[128:129], v[128:129], 1.0 op_sel_hi:[1,0]
	v_exp_f32_e32 v126, v126
	v_exp_f32_e32 v127, v127
	v_pk_add_f32 v[130:131], v[130:131], 1.0 op_sel_hi:[1,0]
	v_pk_add_f32 v[124:125], v[124:125], 1.0 op_sel_hi:[1,0]
	v_rcp_f32_e32 v128, v128
	v_rcp_f32_e32 v129, v129
	v_rcp_f32_e32 v130, v130
	v_rcp_f32_e32 v131, v131
	v_rcp_f32_e32 v124, v124
	v_rcp_f32_e32 v125, v125
	v_pk_add_f32 v[126:127], v[126:127], 1.0 op_sel_hi:[1,0]
	v_or_b32_e32 v155, 16, v153
	v_rcp_f32_e32 v126, v126
	v_rcp_f32_e32 v127, v127
	v_mul_f32_e32 v154, v177, v177
	v_pk_mul_f32 v[120:121], v[120:121], v[154:155] op_sel_hi:[1,0]
	v_pk_mul_f32 v[122:123], v[122:123], v[154:155] op_sel_hi:[1,0]
	v_pk_mul_f32 v[116:117], v[116:117], v[154:155] op_sel_hi:[1,0]
	v_lshl_or_b32 v150, s64, 7, v143
	v_pk_mul_f32 v[118:119], v[118:119], v[154:155] op_sel_hi:[1,0]
	v_pk_mul_f32 v[120:121], v[120:121], v[128:129]
	v_pk_mul_f32 v[122:123], v[122:123], v[130:131]
	v_pk_mul_f32 v[116:117], v[116:117], v[124:125]
	v_ashrrev_i32_e32 v151, 31, v150
	v_pk_mul_f32 v[118:119], v[118:119], v[126:127]
	v_cvt_pk_bf16_f32 v120, v120, v121
	v_cvt_pk_bf16_f32 v121, v122, v123
	v_cvt_pk_bf16_f32 v122, v116, v117
	v_mov_b64_e32 v[116:117], s[22:23]
	v_cvt_pk_bf16_f32 v123, v118, v119
	v_mad_i64_i32 v[124:125], s[34:35], v153, s11, v[116:117]
	v_lshlrev_b64 v[118:119], 1, v[150:151]
	v_lshl_add_u64 v[124:125], v[124:125], 0, v[118:119]
	global_store_dwordx4 v[124:125], v[120:123], off
	v_pk_mul_f32 v[104:105], v[112:113], v[104:105]
	v_pk_mul_f32 v[100:101], v[108:109], v[100:101]
	v_mul_f32_e32 v120, 0xbfb8aa3b, v178
	v_pk_mul_f32 v[124:125], v[112:113], v[120:121] op_sel_hi:[1,0]
	v_pk_mul_f32 v[106:107], v[114:115], v[106:107]
	v_exp_f32_e32 v112, v124
	v_exp_f32_e32 v113, v125
	v_pk_mul_f32 v[124:125], v[108:109], v[120:121] op_sel_hi:[1,0]
	v_pk_mul_f32 v[114:115], v[114:115], v[120:121] op_sel_hi:[1,0]
	v_exp_f32_e32 v108, v124
	v_exp_f32_e32 v109, v125
	v_pk_mul_f32 v[102:103], v[110:111], v[102:103]
	v_pk_mul_f32 v[110:111], v[110:111], v[120:121] op_sel_hi:[1,0]
	v_exp_f32_e32 v114, v114
	v_exp_f32_e32 v115, v115
	v_exp_f32_e32 v110, v110
	v_exp_f32_e32 v111, v111
	v_pk_add_f32 v[112:113], v[112:113], 1.0 op_sel_hi:[1,0]
	v_pk_add_f32 v[108:109], v[108:109], 1.0 op_sel_hi:[1,0]
	v_rcp_f32_e32 v112, v112
	v_rcp_f32_e32 v113, v113
	v_rcp_f32_e32 v108, v108
	v_rcp_f32_e32 v109, v109
	v_mul_f32_e32 v122, v178, v178
	v_pk_add_f32 v[114:115], v[114:115], 1.0 op_sel_hi:[1,0]
	v_pk_add_f32 v[110:111], v[110:111], 1.0 op_sel_hi:[1,0]
	v_pk_mul_f32 v[104:105], v[104:105], v[122:123] op_sel_hi:[1,0]
	v_rcp_f32_e32 v114, v114
	v_rcp_f32_e32 v115, v115
	v_rcp_f32_e32 v110, v110
	v_rcp_f32_e32 v111, v111
	v_pk_mul_f32 v[100:101], v[100:101], v[122:123] op_sel_hi:[1,0]
	v_pk_mul_f32 v[104:105], v[104:105], v[112:113]
	v_pk_mul_f32 v[108:109], v[100:101], v[108:109]
	v_cvt_pk_bf16_f32 v100, v104, v105
	v_mad_i64_i32 v[104:105], s[34:35], v155, s11, v[116:117]
	v_pk_mul_f32 v[106:107], v[106:107], v[122:123] op_sel_hi:[1,0]
	v_pk_mul_f32 v[102:103], v[102:103], v[122:123] op_sel_hi:[1,0]
	v_lshl_add_u64 v[104:105], v[104:105], 0, v[118:119]
	v_pk_mul_f32 v[106:107], v[106:107], v[114:115]
	v_pk_mul_f32 v[110:111], v[102:103], v[110:111]
	v_cvt_pk_bf16_f32 v101, v106, v107
	v_cvt_pk_bf16_f32 v102, v108, v109
	v_pk_mul_f32 v[88:89], v[96:97], v[88:89]
	v_cvt_pk_bf16_f32 v103, v110, v111
	global_store_dwordx4 v[104:105], v[100:103], off
	v_pk_mul_f32 v[84:85], v[92:93], v[84:85]
	v_pk_mul_f32 v[90:91], v[98:99], v[90:91]
	v_mul_f32_e32 v100, 0xbfb8aa3b, v179
	v_pk_mul_f32 v[104:105], v[96:97], v[100:101] op_sel_hi:[1,0]
	v_pk_mul_f32 v[98:99], v[98:99], v[100:101] op_sel_hi:[1,0]
	v_exp_f32_e32 v96, v104
	v_exp_f32_e32 v97, v105
	v_pk_mul_f32 v[104:105], v[92:93], v[100:101] op_sel_hi:[1,0]
	v_pk_mul_f32 v[86:87], v[94:95], v[86:87]
	v_exp_f32_e32 v92, v104
	v_exp_f32_e32 v93, v105
	v_pk_mul_f32 v[94:95], v[94:95], v[100:101] op_sel_hi:[1,0]
	v_exp_f32_e32 v98, v98
	v_exp_f32_e32 v99, v99
	v_exp_f32_e32 v94, v94
	v_exp_f32_e32 v95, v95
	v_pk_add_f32 v[96:97], v[96:97], 1.0 op_sel_hi:[1,0]
	v_pk_add_f32 v[92:93], v[92:93], 1.0 op_sel_hi:[1,0]
	v_rcp_f32_e32 v96, v96
	v_rcp_f32_e32 v97, v97
	v_rcp_f32_e32 v92, v92
	v_rcp_f32_e32 v93, v93
	v_mul_f32_e32 v102, v179, v179
	v_pk_add_f32 v[98:99], v[98:99], 1.0 op_sel_hi:[1,0]
	v_pk_add_f32 v[94:95], v[94:95], 1.0 op_sel_hi:[1,0]
	v_pk_mul_f32 v[88:89], v[88:89], v[102:103] op_sel_hi:[1,0]
	v_rcp_f32_e32 v98, v98
	v_rcp_f32_e32 v99, v99
	v_rcp_f32_e32 v94, v94
	v_rcp_f32_e32 v95, v95
	v_or_b32_e32 v174, 32, v153
	v_pk_mul_f32 v[84:85], v[84:85], v[102:103] op_sel_hi:[1,0]
	v_pk_mul_f32 v[88:89], v[88:89], v[96:97]
	v_pk_mul_f32 v[92:93], v[84:85], v[92:93]
	v_cvt_pk_bf16_f32 v84, v88, v89
	v_mad_i64_i32 v[88:89], s[34:35], v174, s11, v[116:117]
	v_pk_mul_f32 v[90:91], v[90:91], v[102:103] op_sel_hi:[1,0]
	v_pk_mul_f32 v[86:87], v[86:87], v[102:103] op_sel_hi:[1,0]
	v_lshl_add_u64 v[88:89], v[88:89], 0, v[118:119]
	v_pk_mul_f32 v[90:91], v[90:91], v[98:99]
	v_pk_mul_f32 v[94:95], v[86:87], v[94:95]
	v_cvt_pk_bf16_f32 v85, v90, v91
	v_cvt_pk_bf16_f32 v86, v92, v93
	v_pk_mul_f32 v[72:73], v[80:81], v[72:73]
	v_cvt_pk_bf16_f32 v87, v94, v95
	global_store_dwordx4 v[88:89], v[84:87], off
	v_pk_mul_f32 v[68:69], v[76:77], v[68:69]
	v_pk_mul_f32 v[74:75], v[82:83], v[74:75]
	v_mul_f32_e32 v84, 0xbfb8aa3b, v180
	v_pk_mul_f32 v[88:89], v[80:81], v[84:85] op_sel_hi:[1,0]
	v_pk_mul_f32 v[82:83], v[82:83], v[84:85] op_sel_hi:[1,0]
	v_exp_f32_e32 v80, v88
	v_exp_f32_e32 v81, v89
	v_pk_mul_f32 v[88:89], v[76:77], v[84:85] op_sel_hi:[1,0]
	v_pk_mul_f32 v[70:71], v[78:79], v[70:71]
	v_exp_f32_e32 v76, v88
	v_exp_f32_e32 v77, v89
	v_pk_mul_f32 v[78:79], v[78:79], v[84:85] op_sel_hi:[1,0]
	v_exp_f32_e32 v82, v82
	v_exp_f32_e32 v83, v83
	v_exp_f32_e32 v78, v78
	v_exp_f32_e32 v79, v79
	v_pk_add_f32 v[80:81], v[80:81], 1.0 op_sel_hi:[1,0]
	v_pk_add_f32 v[76:77], v[76:77], 1.0 op_sel_hi:[1,0]
	v_rcp_f32_e32 v80, v80
	v_rcp_f32_e32 v81, v81
	v_rcp_f32_e32 v76, v76
	v_rcp_f32_e32 v77, v77
	v_mul_f32_e32 v86, v180, v180
	v_pk_add_f32 v[82:83], v[82:83], 1.0 op_sel_hi:[1,0]
	v_pk_add_f32 v[78:79], v[78:79], 1.0 op_sel_hi:[1,0]
	v_pk_mul_f32 v[72:73], v[72:73], v[86:87] op_sel_hi:[1,0]
	v_rcp_f32_e32 v82, v82
	v_rcp_f32_e32 v83, v83
	v_rcp_f32_e32 v78, v78
	v_rcp_f32_e32 v79, v79
	v_or_b32_e32 v175, 48, v153
	v_pk_mul_f32 v[68:69], v[68:69], v[86:87] op_sel_hi:[1,0]
	v_pk_mul_f32 v[72:73], v[72:73], v[80:81]
	v_pk_mul_f32 v[76:77], v[68:69], v[76:77]
	v_cvt_pk_bf16_f32 v68, v72, v73
	v_mad_i64_i32 v[72:73], s[34:35], v175, s11, v[116:117]
	v_pk_mul_f32 v[74:75], v[74:75], v[86:87] op_sel_hi:[1,0]
	v_pk_mul_f32 v[70:71], v[70:71], v[86:87] op_sel_hi:[1,0]
	v_lshl_add_u64 v[72:73], v[72:73], 0, v[118:119]
	v_pk_mul_f32 v[74:75], v[74:75], v[82:83]
	v_pk_mul_f32 v[78:79], v[70:71], v[78:79]
	v_cvt_pk_bf16_f32 v69, v74, v75
	v_cvt_pk_bf16_f32 v70, v76, v77
	v_pk_mul_f32 v[56:57], v[64:65], v[56:57]
	v_cvt_pk_bf16_f32 v71, v78, v79
	global_store_dwordx4 v[72:73], v[68:71], off
	v_pk_mul_f32 v[52:53], v[60:61], v[52:53]
	v_pk_mul_f32 v[58:59], v[66:67], v[58:59]
	v_mul_f32_e32 v68, 0xbfb8aa3b, v181
	v_pk_mul_f32 v[72:73], v[64:65], v[68:69] op_sel_hi:[1,0]
	v_pk_mul_f32 v[66:67], v[66:67], v[68:69] op_sel_hi:[1,0]
	v_exp_f32_e32 v64, v72
	v_exp_f32_e32 v65, v73
	v_pk_mul_f32 v[72:73], v[60:61], v[68:69] op_sel_hi:[1,0]
	v_pk_mul_f32 v[54:55], v[62:63], v[54:55]
	v_exp_f32_e32 v60, v72
	v_exp_f32_e32 v61, v73
	v_pk_mul_f32 v[62:63], v[62:63], v[68:69] op_sel_hi:[1,0]
	v_exp_f32_e32 v66, v66
	v_exp_f32_e32 v67, v67
	v_exp_f32_e32 v62, v62
	v_exp_f32_e32 v63, v63
	v_pk_add_f32 v[64:65], v[64:65], 1.0 op_sel_hi:[1,0]
	v_pk_add_f32 v[60:61], v[60:61], 1.0 op_sel_hi:[1,0]
	v_rcp_f32_e32 v64, v64
	v_rcp_f32_e32 v65, v65
	v_rcp_f32_e32 v60, v60
	v_rcp_f32_e32 v61, v61
	v_mul_f32_e32 v70, v181, v181
	v_pk_add_f32 v[66:67], v[66:67], 1.0 op_sel_hi:[1,0]
	v_pk_add_f32 v[62:63], v[62:63], 1.0 op_sel_hi:[1,0]
	v_pk_mul_f32 v[56:57], v[56:57], v[70:71] op_sel_hi:[1,0]
	v_rcp_f32_e32 v66, v66
	v_rcp_f32_e32 v67, v67
	v_rcp_f32_e32 v62, v62
	v_rcp_f32_e32 v63, v63
	v_pk_mul_f32 v[52:53], v[52:53], v[70:71] op_sel_hi:[1,0]
	v_pk_mul_f32 v[56:57], v[56:57], v[64:65]
	v_pk_mul_f32 v[60:61], v[52:53], v[60:61]
	v_cvt_pk_bf16_f32 v52, v56, v57
	v_mad_i64_i32 v[56:57], s[34:35], v176, s11, v[116:117]
	v_pk_mul_f32 v[58:59], v[58:59], v[70:71] op_sel_hi:[1,0]
	v_pk_mul_f32 v[54:55], v[54:55], v[70:71] op_sel_hi:[1,0]
	v_lshl_add_u64 v[56:57], v[56:57], 0, v[118:119]
	v_pk_mul_f32 v[58:59], v[58:59], v[66:67]
	v_pk_mul_f32 v[62:63], v[54:55], v[62:63]
	v_cvt_pk_bf16_f32 v53, v58, v59
	v_cvt_pk_bf16_f32 v54, v60, v61
	v_pk_mul_f32 v[40:41], v[48:49], v[40:41]
	v_cvt_pk_bf16_f32 v55, v62, v63
	global_store_dwordx4 v[56:57], v[52:55], off
	v_pk_mul_f32 v[36:37], v[44:45], v[36:37]
	v_pk_mul_f32 v[42:43], v[50:51], v[42:43]
	v_mul_f32_e32 v52, 0xbfb8aa3b, v182
	v_pk_mul_f32 v[56:57], v[48:49], v[52:53] op_sel_hi:[1,0]
	v_pk_mul_f32 v[50:51], v[50:51], v[52:53] op_sel_hi:[1,0]
	v_exp_f32_e32 v48, v56
	v_exp_f32_e32 v49, v57
	v_pk_mul_f32 v[56:57], v[44:45], v[52:53] op_sel_hi:[1,0]
	v_pk_mul_f32 v[38:39], v[46:47], v[38:39]
	v_exp_f32_e32 v44, v56
	v_exp_f32_e32 v45, v57
	v_pk_mul_f32 v[46:47], v[46:47], v[52:53] op_sel_hi:[1,0]
	v_exp_f32_e32 v50, v50
	v_exp_f32_e32 v51, v51
	v_exp_f32_e32 v46, v46
	v_exp_f32_e32 v47, v47
	v_pk_add_f32 v[48:49], v[48:49], 1.0 op_sel_hi:[1,0]
	v_pk_add_f32 v[44:45], v[44:45], 1.0 op_sel_hi:[1,0]
	v_rcp_f32_e32 v48, v48
	v_rcp_f32_e32 v49, v49
	v_rcp_f32_e32 v44, v44
	v_rcp_f32_e32 v45, v45
	v_mul_f32_e32 v54, v182, v182
	v_pk_add_f32 v[50:51], v[50:51], 1.0 op_sel_hi:[1,0]
	v_pk_add_f32 v[46:47], v[46:47], 1.0 op_sel_hi:[1,0]
	v_pk_mul_f32 v[40:41], v[40:41], v[54:55] op_sel_hi:[1,0]
	v_rcp_f32_e32 v50, v50
	v_rcp_f32_e32 v51, v51
	v_rcp_f32_e32 v46, v46
	v_rcp_f32_e32 v47, v47
	v_pk_mul_f32 v[36:37], v[36:37], v[54:55] op_sel_hi:[1,0]
	v_pk_mul_f32 v[40:41], v[40:41], v[48:49]
	v_pk_mul_f32 v[44:45], v[36:37], v[44:45]
	v_cvt_pk_bf16_f32 v36, v40, v41
	v_mad_i64_i32 v[40:41], s[34:35], v148, s11, v[116:117]
	v_pk_mul_f32 v[42:43], v[42:43], v[54:55] op_sel_hi:[1,0]
	v_pk_mul_f32 v[38:39], v[38:39], v[54:55] op_sel_hi:[1,0]
	v_lshl_add_u64 v[40:41], v[40:41], 0, v[118:119]
	v_pk_mul_f32 v[42:43], v[42:43], v[50:51]
	v_pk_mul_f32 v[46:47], v[38:39], v[46:47]
	v_cvt_pk_bf16_f32 v37, v42, v43
	v_cvt_pk_bf16_f32 v38, v44, v45
	v_pk_mul_f32 v[24:25], v[32:33], v[24:25]
	v_cvt_pk_bf16_f32 v39, v46, v47
	global_store_dwordx4 v[40:41], v[36:39], off
	v_pk_mul_f32 v[20:21], v[28:29], v[20:21]
	v_pk_mul_f32 v[26:27], v[34:35], v[26:27]
	v_mul_f32_e32 v36, 0xbfb8aa3b, v149
	v_pk_mul_f32 v[40:41], v[32:33], v[36:37] op_sel_hi:[1,0]
	v_pk_mul_f32 v[34:35], v[34:35], v[36:37] op_sel_hi:[1,0]
	v_exp_f32_e32 v32, v40
	v_exp_f32_e32 v33, v41
	v_pk_mul_f32 v[40:41], v[28:29], v[36:37] op_sel_hi:[1,0]
	v_pk_mul_f32 v[22:23], v[30:31], v[22:23]
	v_exp_f32_e32 v28, v40
	v_exp_f32_e32 v29, v41
	v_pk_mul_f32 v[30:31], v[30:31], v[36:37] op_sel_hi:[1,0]
	v_exp_f32_e32 v34, v34
	v_exp_f32_e32 v35, v35
	v_exp_f32_e32 v30, v30
	v_exp_f32_e32 v31, v31
	v_pk_add_f32 v[32:33], v[32:33], 1.0 op_sel_hi:[1,0]
	v_pk_add_f32 v[28:29], v[28:29], 1.0 op_sel_hi:[1,0]
	v_rcp_f32_e32 v32, v32
	v_rcp_f32_e32 v33, v33
	v_rcp_f32_e32 v28, v28
	v_rcp_f32_e32 v29, v29
	v_mul_f32_e32 v38, v149, v149
	v_pk_add_f32 v[34:35], v[34:35], 1.0 op_sel_hi:[1,0]
	v_pk_add_f32 v[30:31], v[30:31], 1.0 op_sel_hi:[1,0]
	v_pk_mul_f32 v[24:25], v[24:25], v[38:39] op_sel_hi:[1,0]
	v_rcp_f32_e32 v34, v34
	v_rcp_f32_e32 v35, v35
	v_rcp_f32_e32 v30, v30
	v_rcp_f32_e32 v31, v31
	v_pk_mul_f32 v[20:21], v[20:21], v[38:39] op_sel_hi:[1,0]
	v_pk_mul_f32 v[24:25], v[24:25], v[32:33]
	v_pk_mul_f32 v[28:29], v[20:21], v[28:29]
	v_cvt_pk_bf16_f32 v20, v24, v25
	v_mad_i64_i32 v[24:25], s[34:35], v146, s11, v[116:117]
	v_pk_mul_f32 v[26:27], v[26:27], v[38:39] op_sel_hi:[1,0]
	v_pk_mul_f32 v[22:23], v[22:23], v[38:39] op_sel_hi:[1,0]
	v_lshl_add_u64 v[24:25], v[24:25], 0, v[118:119]
	v_pk_mul_f32 v[26:27], v[26:27], v[34:35]
	v_pk_mul_f32 v[30:31], v[22:23], v[30:31]
	v_cvt_pk_bf16_f32 v21, v26, v27
	v_cvt_pk_bf16_f32 v22, v28, v29
	v_pk_mul_f32 v[8:9], v[16:17], v[8:9]
	v_cvt_pk_bf16_f32 v23, v30, v31
	global_store_dwordx4 v[24:25], v[20:23], off
	v_pk_mul_f32 v[4:5], v[12:13], v[4:5]
	v_pk_mul_f32 v[10:11], v[18:19], v[10:11]
	v_mul_f32_e32 v20, 0xbfb8aa3b, v147
	v_pk_mul_f32 v[24:25], v[16:17], v[20:21] op_sel_hi:[1,0]
	v_pk_mul_f32 v[18:19], v[18:19], v[20:21] op_sel_hi:[1,0]
	v_exp_f32_e32 v16, v24
	v_exp_f32_e32 v17, v25
	v_pk_mul_f32 v[24:25], v[12:13], v[20:21] op_sel_hi:[1,0]
	v_pk_mul_f32 v[6:7], v[14:15], v[6:7]
	v_exp_f32_e32 v12, v24
	v_exp_f32_e32 v13, v25
	v_pk_mul_f32 v[14:15], v[14:15], v[20:21] op_sel_hi:[1,0]
	v_exp_f32_e32 v18, v18
	v_exp_f32_e32 v19, v19
	v_exp_f32_e32 v14, v14
	v_exp_f32_e32 v15, v15
	v_pk_add_f32 v[16:17], v[16:17], 1.0 op_sel_hi:[1,0]
	v_pk_add_f32 v[12:13], v[12:13], 1.0 op_sel_hi:[1,0]
	v_rcp_f32_e32 v16, v16
	v_rcp_f32_e32 v17, v17
	v_rcp_f32_e32 v12, v12
	v_rcp_f32_e32 v13, v13
	v_mul_f32_e32 v22, v147, v147
	v_pk_add_f32 v[18:19], v[18:19], 1.0 op_sel_hi:[1,0]
	v_pk_add_f32 v[14:15], v[14:15], 1.0 op_sel_hi:[1,0]
	v_pk_mul_f32 v[8:9], v[8:9], v[22:23] op_sel_hi:[1,0]
	v_rcp_f32_e32 v18, v18
	v_rcp_f32_e32 v19, v19
	v_rcp_f32_e32 v14, v14
	v_rcp_f32_e32 v15, v15
	v_pk_mul_f32 v[4:5], v[4:5], v[22:23] op_sel_hi:[1,0]
	v_pk_mul_f32 v[8:9], v[8:9], v[16:17]
	v_pk_mul_f32 v[12:13], v[4:5], v[12:13]
	v_cvt_pk_bf16_f32 v4, v8, v9
	v_mad_i64_i32 v[8:9], s[34:35], v145, s11, v[116:117]
	v_pk_mul_f32 v[10:11], v[10:11], v[22:23] op_sel_hi:[1,0]
	v_pk_mul_f32 v[6:7], v[6:7], v[22:23] op_sel_hi:[1,0]
	v_lshl_add_u64 v[8:9], v[8:9], 0, v[118:119]
	s_andn2_b64 vcc, exec, s[38:39]
	s_mov_b64 s[34:35], -1
	v_pk_mul_f32 v[10:11], v[10:11], v[18:19]
	v_pk_mul_f32 v[14:15], v[6:7], v[14:15]
	v_cvt_pk_bf16_f32 v5, v10, v11
	v_cvt_pk_bf16_f32 v6, v12, v13
	s_nop 0
	v_cvt_pk_bf16_f32 v7, v14, v15
	global_store_dwordx4 v[8:9], v[4:7], off
	s_cbranch_vccnz .LBB0_165
	s_andn2_b64 vcc, exec, s[26:27]
	s_cbranch_vccnz .LBB0_164
	s_nop 0
	s_branch .LBB0_164

.LBB0_234:
	s_or_b64 exec, exec, s[0:1]
	v_mov_b32_e32 v14, v156
	s_waitcnt lgkmcnt(0)
	s_barrier
	s_and_b64 vcc, exec, s[38:39]
	v_readfirstlane_b32 s36, v14
	v_writelane_b32 v240, s88, 15
	s_cbranch_vccnz .LBB0_347
	v_lshlrev_b32_e32 v1, 4, v14
	v_add_u32_e32 v0, 0x2000, v1
	v_ashrrev_i32_e32 v3, 31, v0
	v_lshrrev_b32_e32 v3, 22, v3
	v_add_u32_e32 v3, v0, v3
	v_ashrrev_i32_e32 v8, 10, v3
	v_mul_i32_i24_e32 v3, 0x400, v8
	v_sub_u32_e32 v0, v0, v3
	v_lshrrev_b32_e32 v3, 4, v0
	v_bitop3_b32 v0, v3, v0, 32 bitop3:0x6c
	v_ashrrev_i32_e32 v3, 31, v0
	v_lshrrev_b32_e32 v3, 26, v3
	s_ashr_i32 s27, s36, 6
	v_add_u32_e32 v3, v0, v3
	v_lshlrev_b32_e32 v4, 3, v8
	s_ashr_i32 s26, s36, 8
	s_lshl_b32 s2, s27, 10
	v_ashrrev_i32_e32 v9, 6, v3
	v_and_b32_e32 v4, -16, v4
	s_add_u32 s19, s88, 0x4200000
	v_readlane_b32 s0, v240, 13
	v_add_u32_e32 v4, v9, v4
	s_addc_u32 s33, s0, 0
	v_and_b32_e32 v5, 3, v9
	s_mov_b32 s0, 0x1ffffe0
	v_lshrrev_b32_e32 v6, 2, v4
	v_lshlrev_b32_e32 v7, 1, v4
	v_and_b32_e32 v3, 0xc0, v3
	v_and_or_b32 v5, v4, s0, v5
	v_and_b32_e32 v6, 4, v6
	v_and_b32_e32 v7, 24, v7
	v_sub_u32_e32 v0, v0, v3
	v_or3_b32 v5, v5, v6, v7
	v_lshlrev_b32_e32 v6, 5, v8
	v_ashrrev_i16_sdwa v0, v220, sext(v0) dst_sel:DWORD dst_unused:UNUSED_PAD src0_sel:DWORD src1_sel:BYTE_0
	v_and_b32_e32 v6, 32, v6
	v_bfe_i32 v10, v0, 0, 16
	v_add_lshl_u32 v3, v6, v10, 1
	v_lshl_add_u32 v0, v5, 7, v3
	v_lshl_add_u32 v148, v4, 12, v3
	v_bfe_i32 v3, v14, 27, 1
	v_lshrrev_b32_e32 v3, 22, v3
	v_add_u32_e32 v3, v1, v3
	v_and_b32_e32 v3, 0xfffffc00, v3
	v_sub_u32_e32 v1, v1, v3
	v_lshrrev_b32_e32 v3, 4, v1
	v_ashrrev_i32_e32 v4, 31, v14
	v_bitop3_b32 v1, v3, v1, 32 bitop3:0x6c
	v_lshrrev_b32_e32 v4, 26, v4
	v_ashrrev_i32_e32 v3, 31, v1
	v_add_u32_e32 v4, v14, v4
	v_lshrrev_b32_e32 v3, 26, v3
	v_ashrrev_i32_e32 v12, 6, v4
	v_add_u32_e32 v3, v1, v3
	v_lshlrev_b32_e32 v4, 3, v12
	v_ashrrev_i32_e32 v11, 6, v3
	v_and_b32_e32 v4, -16, v4
	v_add_u32_e32 v4, v11, v4
	v_and_b32_e32 v5, 3, v11
	v_lshrrev_b32_e32 v6, 2, v4
	v_lshlrev_b32_e32 v7, 1, v4
	v_and_b32_e32 v3, 0xc0, v3
	v_and_or_b32 v5, v4, s0, v5
	v_and_b32_e32 v6, 4, v6
	v_and_b32_e32 v7, 24, v7
	v_sub_u32_e32 v1, v1, v3
	v_or3_b32 v5, v5, v6, v7
	v_lshlrev_b32_e32 v6, 5, v12
	v_ashrrev_i16_sdwa v1, v220, sext(v1) dst_sel:DWORD dst_unused:UNUSED_PAD src0_sel:DWORD src1_sel:BYTE_0
	v_readlane_b32 s0, v241, 55
	v_and_b32_e32 v6, 32, v6
	v_bfe_i32 v13, v1, 0, 16
	v_readlane_b32 s1, v241, 56
	s_add_u32 s34, s19, s0
	v_add_lshl_u32 v1, v6, v13, 1
	s_addc_u32 s35, s33, s1
	s_add_i32 s69, s2, 0
	v_lshl_add_u32 v150, v5, 7, v1
	s_add_i32 m0, s69, 0x10000
	v_lshl_add_u32 v152, v4, 12, v1
	global_load_lds_dwordx4 v150, s[34:35]
	s_add_i32 m0, s69, 0x12000
	s_add_u32 s0, s34, 0x4000
	global_load_lds_dwordx4 v0, s[34:35]
	s_addc_u32 s1, s35, 0
	s_add_i32 m0, s69, 0x14000
	v_mov_b32_e32 v153, v2
	global_load_lds_dwordx4 v150, s[0:1]
	s_add_i32 m0, s69, 0x16000
	v_mov_b32_e32 v149, v2
	global_load_lds_dwordx4 v0, s[0:1]
	v_readlane_b32 s0, v240, 2
	v_readlane_b32 s1, v240, 3
	s_add_u32 s44, s20, s0
	s_addc_u32 s45, s21, s1
	s_add_i32 s71, s69, 0x2000
	s_mov_b32 m0, s69
	s_add_u32 s0, s44, 0x80000
	global_load_lds_dwordx4 v152, s[44:45]
	s_mov_b32 m0, s71
	s_addc_u32 s1, s45, 0
	s_add_i32 s88, s69, 0x4000
	global_load_lds_dwordx4 v148, s[44:45]
	s_mov_b32 m0, s88
	s_add_i32 s96, s69, 0x6000
	global_load_lds_dwordx4 v152, s[0:1]
	s_mov_b32 m0, s96
	s_cmp_eq_u32 s26, 1
	global_load_lds_dwordx4 v148, s[0:1]
	v_lshl_add_u64 v[4:5], s[44:45], 0, v[152:153]
	s_cselect_b64 s[0:1], -1, 0
	s_cmp_lg_u32 s26, 1
	v_lshl_add_u64 v[6:7], s[44:45], 0, v[148:149]
	s_cbranch_scc1 .LBB0_237
	s_nop 0

.LBB0_242:
	s_ashr_i32 s57, s56, 31
	s_lshl_b64 s[36:37], s[56:57], 20
	s_add_u32 s58, s20, s36
	s_addc_u32 s59, s21, s37
	s_and_b64 s[36:37], s[42:43], exec
	s_cselect_b32 s36, s59, s45
	s_cselect_b32 s37, s58, s44
	s_ashr_i32 s55, s54, 31
	s_lshl_b64 s[46:47], s[54:55], 15
	s_add_u32 s60, s19, s46
	s_addc_u32 s61, s33, s47
	s_and_b64 s[46:47], s[42:43], exec
	s_cselect_b32 s55, s61, s35
	s_cselect_b32 s57, s60, s34
	s_add_u32 s63, s34, 0xe0000
	s_addc_u32 vcc_lo, s35, 0
	s_add_u32 s44, s44, 0x80080
	v_mov_b32_e32 v4, 0
	s_addc_u32 s45, s45, 0
	s_mov_b32 vcc_hi, -2
	v_mov_b32_e32 v5, v4
	v_mov_b32_e32 v6, v4
	v_mov_b32_e32 v7, v4
	v_mov_b32_e32 v8, v4
	v_mov_b32_e32 v9, v4
	v_mov_b32_e32 v10, v4
	v_mov_b32_e32 v11, v4
	v_mov_b32_e32 v20, v4
	v_mov_b32_e32 v21, v4
	v_mov_b32_e32 v22, v4
	v_mov_b32_e32 v23, v4
	v_mov_b32_e32 v24, v4
	v_mov_b32_e32 v25, v4
	v_mov_b32_e32 v26, v4
	v_mov_b32_e32 v27, v4
	v_mov_b32_e32 v36, v4
	v_mov_b32_e32 v37, v4
	s_waitcnt lgkmcnt(0)
	v_mov_b32_e32 v38, v4
	v_mov_b32_e32 v39, v4
	v_mov_b32_e32 v40, v4
	v_mov_b32_e32 v41, v4
	v_mov_b32_e32 v42, v4
	v_mov_b32_e32 v43, v4
	v_mov_b32_e32 v52, v4
	v_mov_b32_e32 v53, v4
	v_mov_b32_e32 v54, v4
	v_mov_b32_e32 v55, v4
	v_mov_b32_e32 v56, v4
	v_mov_b32_e32 v57, v4
	v_mov_b32_e32 v58, v4
	v_mov_b32_e32 v59, v4
	v_mov_b32_e32 v12, v4
	v_mov_b32_e32 v13, v4
	v_mov_b32_e32 v14, v4
	v_mov_b32_e32 v15, v4
	v_mov_b32_e32 v16, v4
	v_mov_b32_e32 v17, v4
	v_mov_b32_e32 v18, v4
	v_mov_b32_e32 v19, v4
	v_mov_b32_e32 v28, v4
	v_mov_b32_e32 v29, v4
	v_mov_b32_e32 v30, v4
	v_mov_b32_e32 v31, v4
	v_mov_b32_e32 v32, v4
	v_mov_b32_e32 v33, v4
	v_mov_b32_e32 v34, v4
	v_mov_b32_e32 v35, v4
	v_mov_b32_e32 v44, v4
	v_mov_b32_e32 v45, v4
	v_mov_b32_e32 v46, v4
	v_mov_b32_e32 v47, v4
	v_mov_b32_e32 v48, v4
	v_mov_b32_e32 v49, v4
	v_mov_b32_e32 v50, v4
	v_mov_b32_e32 v51, v4
	v_mov_b32_e32 v60, v4
	v_mov_b32_e32 v61, v4
	v_mov_b32_e32 v62, v4
	v_mov_b32_e32 v63, v4
	v_mov_b32_e32 v64, v4
	v_mov_b32_e32 v65, v4
	v_mov_b32_e32 v66, v4
	v_mov_b32_e32 v67, v4
	v_mov_b32_e32 v68, v4
	v_mov_b32_e32 v69, v4
	v_mov_b32_e32 v70, v4
	v_mov_b32_e32 v71, v4
	v_mov_b32_e32 v72, v4
	v_mov_b32_e32 v73, v4
	v_mov_b32_e32 v74, v4
	v_mov_b32_e32 v75, v4
	v_mov_b32_e32 v84, v4
	v_mov_b32_e32 v85, v4
	v_mov_b32_e32 v86, v4
	v_mov_b32_e32 v87, v4
	v_mov_b32_e32 v88, v4
	v_mov_b32_e32 v89, v4
	v_mov_b32_e32 v90, v4
	v_mov_b32_e32 v91, v4
	v_mov_b32_e32 v100, v4
	v_mov_b32_e32 v101, v4
	v_mov_b32_e32 v102, v4
	v_mov_b32_e32 v103, v4
	v_mov_b32_e32 v104, v4
	v_mov_b32_e32 v105, v4
	v_mov_b32_e32 v106, v4
	v_mov_b32_e32 v107, v4
	v_mov_b32_e32 v116, v4
	v_mov_b32_e32 v117, v4
	v_mov_b32_e32 v118, v4
	v_mov_b32_e32 v119, v4
	v_mov_b32_e32 v120, v4
	v_mov_b32_e32 v121, v4
	v_mov_b32_e32 v122, v4
	v_mov_b32_e32 v123, v4
	v_mov_b32_e32 v76, v4
	v_mov_b32_e32 v77, v4
	v_mov_b32_e32 v78, v4
	v_mov_b32_e32 v79, v4
	v_mov_b32_e32 v80, v4
	v_mov_b32_e32 v81, v4
	v_mov_b32_e32 v82, v4
	v_mov_b32_e32 v83, v4
	v_mov_b32_e32 v92, v4
	v_mov_b32_e32 v93, v4
	v_mov_b32_e32 v94, v4
	v_mov_b32_e32 v95, v4
	v_mov_b32_e32 v96, v4
	v_mov_b32_e32 v97, v4
	v_mov_b32_e32 v98, v4
	v_mov_b32_e32 v99, v4
	v_mov_b32_e32 v108, v4
	v_mov_b32_e32 v109, v4
	v_mov_b32_e32 v110, v4
	v_mov_b32_e32 v111, v4
	v_mov_b32_e32 v112, v4
	v_mov_b32_e32 v113, v4
	v_mov_b32_e32 v114, v4
	v_mov_b32_e32 v115, v4
	v_mov_b32_e32 v124, v4
	v_mov_b32_e32 v125, v4
	v_mov_b32_e32 v126, v4
	v_mov_b32_e32 v127, v4
	v_mov_b32_e32 v128, v4
	v_mov_b32_e32 v129, v4
	v_mov_b32_e32 v130, v4
	v_mov_b32_e32 v131, v4
	v_readfirstlane_b32 s101, v156
	s_bfe_u32 s101, s101, 0x10008
.LBB0_243:
	s_add_u32 s34, s44, 0xfff80080
	s_addc_u32 s35, s45, -1
	s_add_i32 s52, 0, 0x10000
	s_cmp_eq_u32 vcc_hi, 28
	s_cselect_b32 s47, s36, s35
	s_cselect_b32 s46, s37, s34
	s_cselect_b32 s35, s55, vcc_lo
	s_cselect_b32 s34, s57, s63
	s_add_i32 s68, 0, 0x14000
	v_add_u32_e32 v144, s52, v155
	v_add_u32_e32 v180, s68, v155
	ds_read_b128 v[132:135], v144
	ds_read_b128 v[136:139], v144 offset:1024
	ds_read_b128 v[140:143], v144 offset:2048
	ds_read_b128 v[144:147], v144 offset:3072
	ds_read_b128 v[176:179], v180
	ds_read_b128 v[182:185], v180 offset:1024
	ds_read_b128 v[186:189], v180 offset:2048
	ds_read_b128 v[190:193], v180 offset:3072
	v_lshl_add_u64 v[218:219], s[44:45], 0, v[172:173]
	s_add_i32 m0, s69, 0xc000
	ds_read_b128 v[194:197], v181
	ds_read_b128 v[198:201], v181 offset:1024
	ds_read_b128 v[202:205], v181 offset:2048
	ds_read_b128 v[206:209], v181 offset:3072
	ds_read_b128 v[210:213], v181 offset:4096
	ds_read_b128 v[214:217], v181 offset:5120
	ds_read_b128 v[228:231], v181 offset:6144
	ds_read_b128 v[232:235], v181 offset:7168
	global_load_lds_dwordx4 v[218:219], off
	v_lshl_add_u64 v[218:219], s[44:45], 0, v[174:175]
	s_add_i32 m0, s69, 0xe000
	s_nop 0
	global_load_lds_dwordx4 v[218:219], off
	s_waitcnt vmcnt(8)
	s_waitcnt lgkmcnt(0)
	s_cmp_eq_u32 s101, 0
	s_cbranch_scc1 .LnbA_5
	s_barrier
	s_setprio 2
	s_branch .Lnb_9

.Lnb_9:
	v_mfma_f32_16x16x32_bf16 v[128:131], v[132:135], v[194:197], v[128:131]
	v_mfma_f32_16x16x32_bf16 v[128:131], v[136:139], v[198:201], v[128:131]
	v_mfma_f32_16x16x32_bf16 v[124:127], v[140:143], v[194:197], v[124:127]
	v_mfma_f32_16x16x32_bf16 v[124:127], v[144:147], v[198:201], v[124:127]
	v_mfma_f32_16x16x32_bf16 v[108:111], v[140:143], v[202:205], v[108:111]
	v_mfma_f32_16x16x32_bf16 v[108:111], v[144:147], v[206:209], v[108:111]
	v_mfma_f32_16x16x32_bf16 v[112:115], v[132:135], v[202:205], v[112:115]
	v_mfma_f32_16x16x32_bf16 v[112:115], v[136:139], v[206:209], v[112:115]
	v_mfma_f32_16x16x32_bf16 v[96:99], v[132:135], v[210:213], v[96:99]
	v_mfma_f32_16x16x32_bf16 v[96:99], v[136:139], v[214:217], v[96:99]
	v_mfma_f32_16x16x32_bf16 v[92:95], v[140:143], v[210:213], v[92:95]
	v_mfma_f32_16x16x32_bf16 v[92:95], v[144:147], v[214:217], v[92:95]
	v_mfma_f32_16x16x32_bf16 v[76:79], v[140:143], v[228:231], v[76:79]
	v_mfma_f32_16x16x32_bf16 v[76:79], v[144:147], v[232:235], v[76:79]
	v_mfma_f32_16x16x32_bf16 v[80:83], v[132:135], v[228:231], v[80:83]
	v_mfma_f32_16x16x32_bf16 v[80:83], v[136:139], v[232:235], v[80:83]
	v_mfma_f32_16x16x32_bf16 v[120:123], v[176:179], v[194:197], v[120:123]
	v_mfma_f32_16x16x32_bf16 v[120:123], v[182:185], v[198:201], v[120:123]
	v_mfma_f32_16x16x32_bf16 v[116:119], v[186:189], v[194:197], v[116:119]
	v_mfma_f32_16x16x32_bf16 v[116:119], v[190:193], v[198:201], v[116:119]
	v_mfma_f32_16x16x32_bf16 v[100:103], v[186:189], v[202:205], v[100:103]
	v_mfma_f32_16x16x32_bf16 v[100:103], v[190:193], v[206:209], v[100:103]
	v_mfma_f32_16x16x32_bf16 v[104:107], v[176:179], v[202:205], v[104:107]
	v_mfma_f32_16x16x32_bf16 v[104:107], v[182:185], v[206:209], v[104:107]
	v_mfma_f32_16x16x32_bf16 v[88:91], v[176:179], v[210:213], v[88:91]
	v_mfma_f32_16x16x32_bf16 v[88:91], v[182:185], v[214:217], v[88:91]
	v_mfma_f32_16x16x32_bf16 v[84:87], v[186:189], v[210:213], v[84:87]
	v_mfma_f32_16x16x32_bf16 v[84:87], v[190:193], v[214:217], v[84:87]
	v_mfma_f32_16x16x32_bf16 v[68:71], v[186:189], v[228:231], v[68:71]
	v_mfma_f32_16x16x32_bf16 v[68:71], v[190:193], v[232:235], v[68:71]
	v_mfma_f32_16x16x32_bf16 v[72:75], v[176:179], v[228:231], v[72:75]
	v_mfma_f32_16x16x32_bf16 v[72:75], v[182:185], v[232:235], v[72:75]
	s_setprio 0
	s_cmp_lg_u32 s101, 0
	s_cbranch_scc1 .Lnb_10
	s_barrier
.Lnb_10:
	s_add_i32 s52, s52, s2
	v_lshl_add_u64 v[218:219], s[34:35], 0, v[150:151]
	s_mov_b32 m0, s52
	ds_read_b128 v[194:197], v181 offset:16384
	ds_read_b128 v[198:201], v181 offset:17408
	ds_read_b128 v[202:205], v181 offset:18432
	ds_read_b128 v[206:209], v181 offset:19456
	ds_read_b128 v[210:213], v181 offset:20480
	ds_read_b128 v[214:217], v181 offset:21504
	ds_read_b128 v[228:231], v181 offset:22528
	ds_read_b128 v[232:235], v181 offset:23552
	global_load_lds_dwordx4 v[218:219], off
	s_add_i32 m0, s52, 0x2000
	s_add_u32 s52, s34, 0x4000
	v_lshl_add_u64 v[218:219], s[34:35], 0, v[0:1]
	s_addc_u32 s53, s35, 0
	s_add_i32 s68, s68, s2
	global_load_lds_dwordx4 v[218:219], off
	v_lshl_add_u64 v[218:219], s[52:53], 0, v[150:151]
	s_mov_b32 m0, s68
	v_lshl_add_u64 v[236:237], s[46:47], 0, v[148:149]
	global_load_lds_dwordx4 v[218:219], off
	v_lshl_add_u64 v[218:219], s[52:53], 0, v[0:1]
	s_add_i32 m0, s68, 0x2000
	s_nop 0
	global_load_lds_dwordx4 v[218:219], off
	v_lshl_add_u64 v[218:219], s[46:47], 0, v[152:153]
	s_mov_b32 m0, s69
	s_nop 0
	global_load_lds_dwordx4 v[218:219], off
	s_mov_b32 m0, s71
	s_nop 0
	global_load_lds_dwordx4 v[236:237], off
	s_waitcnt vmcnt(8)
	s_waitcnt lgkmcnt(0)
	s_cmp_eq_u32 s101, 0
	s_cbranch_scc1 .LnbA_6
	s_barrier
	s_setprio 2
	s_branch .Lnb_11

.Lnb_11:
	v_mfma_f32_16x16x32_bf16 v[64:67], v[132:135], v[194:197], v[64:67]
	v_mfma_f32_16x16x32_bf16 v[64:67], v[136:139], v[198:201], v[64:67]
	v_mfma_f32_16x16x32_bf16 v[60:63], v[140:143], v[194:197], v[60:63]
	v_mfma_f32_16x16x32_bf16 v[60:63], v[144:147], v[198:201], v[60:63]
	v_mfma_f32_16x16x32_bf16 v[44:47], v[140:143], v[202:205], v[44:47]
	v_mfma_f32_16x16x32_bf16 v[44:47], v[144:147], v[206:209], v[44:47]
	v_mfma_f32_16x16x32_bf16 v[48:51], v[132:135], v[202:205], v[48:51]
	v_mfma_f32_16x16x32_bf16 v[48:51], v[136:139], v[206:209], v[48:51]
	v_mfma_f32_16x16x32_bf16 v[32:35], v[132:135], v[210:213], v[32:35]
	v_mfma_f32_16x16x32_bf16 v[32:35], v[136:139], v[214:217], v[32:35]
	v_mfma_f32_16x16x32_bf16 v[28:31], v[140:143], v[210:213], v[28:31]
	v_mfma_f32_16x16x32_bf16 v[28:31], v[144:147], v[214:217], v[28:31]
	v_mfma_f32_16x16x32_bf16 v[12:15], v[140:143], v[228:231], v[12:15]
	v_mfma_f32_16x16x32_bf16 v[12:15], v[144:147], v[232:235], v[12:15]
	v_mfma_f32_16x16x32_bf16 v[16:19], v[132:135], v[228:231], v[16:19]
	v_mfma_f32_16x16x32_bf16 v[16:19], v[136:139], v[232:235], v[16:19]
	v_mfma_f32_16x16x32_bf16 v[56:59], v[176:179], v[194:197], v[56:59]
	v_mfma_f32_16x16x32_bf16 v[56:59], v[182:185], v[198:201], v[56:59]
	v_mfma_f32_16x16x32_bf16 v[52:55], v[186:189], v[194:197], v[52:55]
	v_mfma_f32_16x16x32_bf16 v[52:55], v[190:193], v[198:201], v[52:55]
	v_mfma_f32_16x16x32_bf16 v[36:39], v[186:189], v[202:205], v[36:39]
	v_mfma_f32_16x16x32_bf16 v[36:39], v[190:193], v[206:209], v[36:39]
	v_mfma_f32_16x16x32_bf16 v[40:43], v[176:179], v[202:205], v[40:43]
	v_mfma_f32_16x16x32_bf16 v[40:43], v[182:185], v[206:209], v[40:43]
	v_mfma_f32_16x16x32_bf16 v[24:27], v[176:179], v[210:213], v[24:27]
	v_mfma_f32_16x16x32_bf16 v[24:27], v[182:185], v[214:217], v[24:27]
	v_mfma_f32_16x16x32_bf16 v[20:23], v[186:189], v[210:213], v[20:23]
	v_mfma_f32_16x16x32_bf16 v[20:23], v[190:193], v[214:217], v[20:23]
	v_mfma_f32_16x16x32_bf16 v[4:7], v[186:189], v[228:231], v[4:7]
	v_mfma_f32_16x16x32_bf16 v[4:7], v[190:193], v[232:235], v[4:7]
	v_mfma_f32_16x16x32_bf16 v[8:11], v[176:179], v[228:231], v[8:11]
	v_mfma_f32_16x16x32_bf16 v[8:11], v[182:185], v[232:235], v[8:11]
	s_setprio 0
	s_cmp_lg_u32 s101, 0
	s_cbranch_scc1 .Lnb_12
	s_barrier
.Lnb_12:
	s_add_i32 s52, 0, 0x18000
	s_add_i32 s53, 0, 0x1c000
	v_add_u32_e32 v144, s52, v155
	v_add_u32_e32 v180, s53, v155
	ds_read_b128 v[132:135], v144
	ds_read_b128 v[136:139], v144 offset:1024
	ds_read_b128 v[140:143], v144 offset:2048
	ds_read_b128 v[144:147], v144 offset:3072
	ds_read_b128 v[176:179], v180
	ds_read_b128 v[182:185], v180 offset:1024
	ds_read_b128 v[186:189], v180 offset:2048
	ds_read_b128 v[190:193], v180 offset:3072
	s_add_u32 s46, s46, 0x80000
	s_addc_u32 s47, s47, 0
	s_mov_b32 m0, s88
	v_lshl_add_u64 v[238:239], s[46:47], 0, v[152:153]
	ds_read_b128 v[194:197], v181 offset:32768
	ds_read_b128 v[198:201], v181 offset:33792
	ds_read_b128 v[202:205], v181 offset:34816
	ds_read_b128 v[206:209], v181 offset:35840
	ds_read_b128 v[210:213], v181 offset:36864
	ds_read_b128 v[214:217], v181 offset:37888
	ds_read_b128 v[228:231], v181 offset:38912
	ds_read_b128 v[232:235], v181 offset:39936
	global_load_lds_dwordx4 v[238:239], off
	v_lshl_add_u64 v[238:239], s[46:47], 0, v[148:149]
	s_mov_b32 m0, s96
	s_nop 0
	global_load_lds_dwordx4 v[238:239], off
	s_waitcnt vmcnt(8)
	s_waitcnt lgkmcnt(0)
	s_cmp_eq_u32 s101, 0
	s_cbranch_scc1 .LnbA_7
	s_barrier
	s_setprio 2
	s_branch .Lnb_13

.Lnb_14:
	s_add_u32 s46, s34, 0x70000
	s_addc_u32 s47, s35, 0
	s_add_i32 s52, s52, s2
	v_lshl_add_u64 v[238:239], s[46:47], 0, v[150:151]
	s_mov_b32 m0, s52
	ds_read_b128 v[194:197], v181 offset:49152
	ds_read_b128 v[198:201], v181 offset:50176
	ds_read_b128 v[202:205], v181 offset:51200
	ds_read_b128 v[206:209], v181 offset:52224
	ds_read_b128 v[210:213], v181 offset:53248
	ds_read_b128 v[214:217], v181 offset:54272
	ds_read_b128 v[228:231], v181 offset:55296
	ds_read_b128 v[232:235], v181 offset:56320
	global_load_lds_dwordx4 v[238:239], off
	s_add_i32 m0, s52, 0x2000
	s_add_u32 s34, s34, 0x74000
	v_lshl_add_u64 v[238:239], s[46:47], 0, v[0:1]
	s_addc_u32 s35, s35, 0
	s_add_i32 s46, s53, s2
	global_load_lds_dwordx4 v[238:239], off
	v_lshl_add_u64 v[238:239], s[34:35], 0, v[150:151]
	s_mov_b32 m0, s46
	v_lshl_add_u64 v[218:219], v[218:219], 0, s[14:15]
	global_load_lds_dwordx4 v[238:239], off
	v_lshl_add_u64 v[238:239], s[34:35], 0, v[0:1]
	s_add_i32 m0, s46, 0x2000
	s_nop 0
	global_load_lds_dwordx4 v[238:239], off
	s_mov_b32 m0, s97
	s_nop 0
	global_load_lds_dwordx4 v[218:219], off
	v_lshl_add_u64 v[218:219], v[236:237], 0, s[14:15]
	s_mov_b32 m0, s76
	s_nop 0
	global_load_lds_dwordx4 v[218:219], off
	s_waitcnt vmcnt(8)
	s_waitcnt lgkmcnt(0)
	s_cmp_eq_u32 s101, 0
	s_cbranch_scc1 .LnbA_8
	s_barrier
	s_setprio 2
	s_branch .Lnb_15

.Lnb_16:
	s_add_i32 vcc_hi, vcc_hi, 2
	s_add_u32 s63, s63, 0xe0000
	s_addc_u32 vcc_lo, vcc_lo, 0
	s_add_u32 s44, s44, 0x100
	s_addc_u32 s45, s45, 0
	s_cmp_gt_u32 vcc_hi, 29
	s_cbranch_scc0 .LBB0_243
	s_and_b64 vcc, exec, s[28:29]
	s_nop 0
	s_barrier

.LBB0_342:
	s_andn2_b64 vcc, exec, s[42:43]
	s_mov_b64 s[34:35], -1
	s_cbranch_vccnz .LBB0_239
	s_andn2_b64 vcc, exec, s[0:1]
	s_cbranch_vccnz .LBB0_238
	s_nop 0
	s_branch .LBB0_238

.LBB0_544:
	v_readlane_b32 s26, v241, 48
	v_mov_b32_e32 v14, v156
	v_readlane_b32 s27, v241, 49
	s_add_i32 s70, s70, 1
	s_andn2_b64 vcc, exec, s[26:27]
	v_readfirstlane_b32 s36, v14
	s_cbranch_vccnz .LBB0_582
	v_lshlrev_b32_e32 v1, 4, v14
	v_add_u32_e32 v0, 0x2000, v1
	v_ashrrev_i32_e32 v3, 31, v0
	v_lshrrev_b32_e32 v3, 22, v3
	v_add_u32_e32 v3, v0, v3
	v_ashrrev_i32_e32 v3, 10, v3
	v_mul_i32_i24_e32 v4, 0x400, v3
	v_sub_u32_e32 v0, v0, v4
	v_lshrrev_b32_e32 v4, 4, v0
	v_bitop3_b32 v0, v4, v0, 32 bitop3:0x6c
	v_ashrrev_i32_e32 v4, 31, v0
	v_lshrrev_b32_e32 v4, 26, v4
	v_add_u32_e32 v4, v0, v4
	v_lshlrev_b32_e32 v6, 3, v3
	v_ashrrev_i32_e32 v5, 6, v4
	v_and_b32_e32 v6, -16, v6
	s_add_u32 s2, s88, s28
	v_readlane_b32 s1, v240, 13
	v_add_u32_e32 v6, v5, v6
	s_addc_u32 s19, s1, s29
	v_and_b32_e32 v5, 3, v5
	s_mov_b32 s1, 0x1ffffe0
	v_lshrrev_b32_e32 v7, 2, v6
	v_lshlrev_b32_e32 v8, 1, v6
	v_and_or_b32 v5, v6, s1, v5
	v_and_b32_e32 v7, 4, v7
	v_and_b32_e32 v8, 24, v8
	v_lshlrev_b32_e32 v3, 5, v3
	v_or3_b32 v5, v5, v7, v8
	v_and_b32_e32 v8, 32, v3
	v_and_b32_e32 v3, 0xc0, v4
	v_sub_u32_e32 v0, v0, v3
	v_ashrrev_i16_sdwa v0, v220, sext(v0) dst_sel:DWORD dst_unused:UNUSED_PAD src0_sel:DWORD src1_sel:BYTE_0
	v_bfe_i32 v9, v0, 0, 16
	v_add_u32_e32 v3, v8, v9
	v_mul_lo_u32 v10, v6, s37
	v_lshlrev_b32_e32 v0, 1, v3
	v_add_lshl_u32 v172, v3, v10, 1
	v_bfe_i32 v3, v14, 27, 1
	v_lshrrev_b32_e32 v3, 22, v3
	v_add_u32_e32 v3, v1, v3
	v_and_b32_e32 v3, 0xfffffc00, v3
	v_sub_u32_e32 v1, v1, v3
	v_lshl_add_u32 v0, v5, 7, v0
	v_lshrrev_b32_e32 v3, 4, v1
	v_ashrrev_i32_e32 v5, 31, v14
	v_bitop3_b32 v1, v3, v1, 32 bitop3:0x6c
	v_lshrrev_b32_e32 v5, 26, v5
	v_ashrrev_i32_e32 v3, 31, v1
	v_add_u32_e32 v5, v14, v5
	v_lshrrev_b32_e32 v3, 26, v3
	v_ashrrev_i32_e32 v5, 6, v5
	v_add_u32_e32 v3, v1, v3
	v_lshlrev_b32_e32 v6, 3, v5
	v_ashrrev_i32_e32 v4, 6, v3
	v_and_b32_e32 v6, -16, v6
	v_add_u32_e32 v6, v4, v6
	v_and_b32_e32 v3, 0xc0, v3
	v_and_b32_e32 v4, 3, v4
	v_lshrrev_b32_e32 v7, 2, v6
	v_lshlrev_b32_e32 v11, 1, v6
	v_sub_u32_e32 v1, v1, v3
	s_ashr_i32 s39, s36, 6
	v_and_or_b32 v4, v6, s1, v4
	v_and_b32_e32 v7, 4, v7
	v_and_b32_e32 v11, 24, v11
	v_lshlrev_b32_e32 v5, 5, v5
	v_ashrrev_i16_sdwa v1, v220, sext(v1) dst_sel:DWORD dst_unused:UNUSED_PAD src0_sel:DWORD src1_sel:BYTE_0
	s_ashr_i32 s38, s36, 8
	s_lshl_b32 s26, s37, 8
	s_lshl_b32 s33, s37, 9
	s_lshl_b32 s58, s39, 10
	v_or3_b32 v4, v4, v7, v11
	v_and_b32_e32 v11, 32, v5
	v_bfe_i32 v12, v1, 0, 16
	v_readlane_b32 s28, v241, 58
	v_add_u32_e32 v1, v11, v12
	v_readlane_b32 s29, v241, 59
	s_add_u32 s34, s2, s28
	v_lshlrev_b32_e32 v3, 1, v1
	s_addc_u32 s35, s19, s29
	s_add_i32 s59, s58, 0
	v_lshl_add_u32 v174, v4, 7, v3
	s_add_i32 m0, s59, 0x10000
	v_readlane_b32 s27, v241, 53
	global_load_lds_dwordx4 v174, s[34:35]
	s_add_i32 m0, s59, 0x12000
	s_add_u32 s28, s34, 0x4000
	global_load_lds_dwordx4 v0, s[34:35]
	s_addc_u32 s29, s35, 0
	s_add_i32 m0, s59, 0x14000
	s_mul_hi_i32 s1, s33, s27
	s_mul_i32 s27, s33, s27
	global_load_lds_dwordx4 v174, s[28:29]
	s_add_i32 m0, s59, 0x16000
	s_add_u32 s56, s22, s27
	v_mul_lo_u32 v13, v6, s37
	s_addc_u32 s57, s23, s1
	s_add_i32 s60, s59, 0x2000
	v_add_lshl_u32 v176, v1, v13, 1
	global_load_lds_dwordx4 v0, s[28:29]
	s_mov_b32 m0, s59
	s_add_u32 s28, s56, s26
	global_load_lds_dwordx4 v176, s[56:57]
	s_mov_b32 m0, s60
	s_addc_u32 s29, s57, 0
	s_add_i32 s61, s59, 0x4000
	global_load_lds_dwordx4 v172, s[56:57]
	s_mov_b32 m0, s61
	s_add_i32 s62, s59, 0x6000
	global_load_lds_dwordx4 v176, s[28:29]
	s_mov_b32 m0, s62
	v_mov_b32_e32 v177, v2
	global_load_lds_dwordx4 v172, s[28:29]
	v_mov_b32_e32 v173, v2
	s_cmp_eq_u32 s38, 1
	s_mov_b32 s27, s65
	v_lshl_add_u64 v[4:5], s[56:57], 0, v[176:177]
	s_cselect_b64 s[28:29], -1, 0
	s_cmp_lg_u32 s38, 1
	v_lshl_add_u64 v[6:7], s[56:57], 0, v[172:173]
	s_cbranch_scc1 .LBB0_547
	s_nop 0

.LBB0_558:
	s_ashr_i32 s49, s48, 31
	s_lshl_b64 s[36:37], s[48:49], 15
	s_add_u32 s54, s2, s36
	s_addc_u32 s55, s19, s37
	s_and_b64 s[36:37], s[42:43], exec
	s_cselect_b32 s36, s55, s35
	s_cselect_b32 s37, s54, s34
	s_add_u32 s49, s34, 0x80000
	s_addc_u32 s97, s35, 0
	s_add_u32 s42, s56, 0x80
	v_mov_b32_e32 v4, 0
	s_addc_u32 s43, s57, 0
	s_mov_b32 s34, 0
	s_waitcnt lgkmcnt(0)
	v_mov_b32_e32 v5, v4
	v_mov_b32_e32 v6, v4
	v_mov_b32_e32 v7, v4
	v_mov_b32_e32 v8, v4
	v_mov_b32_e32 v9, v4
	v_mov_b32_e32 v10, v4
	v_mov_b32_e32 v11, v4
	v_mov_b32_e32 v20, v4
	v_mov_b32_e32 v21, v4
	v_mov_b32_e32 v22, v4
	v_mov_b32_e32 v23, v4
	v_mov_b32_e32 v24, v4
	v_mov_b32_e32 v25, v4
	v_mov_b32_e32 v26, v4
	v_mov_b32_e32 v27, v4
	v_mov_b32_e32 v36, v4
	v_mov_b32_e32 v37, v4
	v_mov_b32_e32 v38, v4
	v_mov_b32_e32 v39, v4
	v_mov_b32_e32 v40, v4
	v_mov_b32_e32 v41, v4
	v_mov_b32_e32 v42, v4
	v_mov_b32_e32 v43, v4
	v_mov_b32_e32 v52, v4
	v_mov_b32_e32 v53, v4
	v_mov_b32_e32 v54, v4
	v_mov_b32_e32 v55, v4
	v_mov_b32_e32 v56, v4
	v_mov_b32_e32 v57, v4
	v_mov_b32_e32 v58, v4
	v_mov_b32_e32 v59, v4
	v_mov_b32_e32 v12, v4
	v_mov_b32_e32 v13, v4
	v_mov_b32_e32 v14, v4
	v_mov_b32_e32 v15, v4
	v_mov_b32_e32 v16, v4
	v_mov_b32_e32 v17, v4
	v_mov_b32_e32 v18, v4
	v_mov_b32_e32 v19, v4
	v_mov_b32_e32 v28, v4
	v_mov_b32_e32 v29, v4
	v_mov_b32_e32 v30, v4
	v_mov_b32_e32 v31, v4
	v_mov_b32_e32 v32, v4
	v_mov_b32_e32 v33, v4
	v_mov_b32_e32 v34, v4
	v_mov_b32_e32 v35, v4
	v_mov_b32_e32 v44, v4
	v_mov_b32_e32 v45, v4
	v_mov_b32_e32 v46, v4
	v_mov_b32_e32 v47, v4
	v_mov_b32_e32 v48, v4
	v_mov_b32_e32 v49, v4
	v_mov_b32_e32 v50, v4
	v_mov_b32_e32 v51, v4
	v_mov_b32_e32 v60, v4
	v_mov_b32_e32 v61, v4
	v_mov_b32_e32 v62, v4
	v_mov_b32_e32 v63, v4
	v_mov_b32_e32 v64, v4
	v_mov_b32_e32 v65, v4
	v_mov_b32_e32 v66, v4
	v_mov_b32_e32 v67, v4
	v_mov_b32_e32 v68, v4
	v_mov_b32_e32 v69, v4
	v_mov_b32_e32 v70, v4
	v_mov_b32_e32 v71, v4
	v_mov_b32_e32 v72, v4
	v_mov_b32_e32 v73, v4
	v_mov_b32_e32 v74, v4
	v_mov_b32_e32 v75, v4
	v_mov_b32_e32 v84, v4
	v_mov_b32_e32 v85, v4
	v_mov_b32_e32 v86, v4
	v_mov_b32_e32 v87, v4
	v_mov_b32_e32 v88, v4
	v_mov_b32_e32 v89, v4
	v_mov_b32_e32 v90, v4
	v_mov_b32_e32 v91, v4
	v_mov_b32_e32 v100, v4
	v_mov_b32_e32 v101, v4
	v_mov_b32_e32 v102, v4
	v_mov_b32_e32 v103, v4
	v_mov_b32_e32 v104, v4
	v_mov_b32_e32 v105, v4
	v_mov_b32_e32 v106, v4
	v_mov_b32_e32 v107, v4
	v_mov_b32_e32 v128, v4
	v_mov_b32_e32 v129, v4
	v_mov_b32_e32 v130, v4
	v_mov_b32_e32 v131, v4
	v_mov_b32_e32 v132, v4
	v_mov_b32_e32 v133, v4
	v_mov_b32_e32 v134, v4
	v_mov_b32_e32 v135, v4
	v_mov_b32_e32 v76, v4
	v_mov_b32_e32 v77, v4
	v_mov_b32_e32 v78, v4
	v_mov_b32_e32 v79, v4
	v_mov_b32_e32 v80, v4
	v_mov_b32_e32 v81, v4
	v_mov_b32_e32 v82, v4
	v_mov_b32_e32 v83, v4
	v_mov_b32_e32 v92, v4
	v_mov_b32_e32 v93, v4
	v_mov_b32_e32 v94, v4
	v_mov_b32_e32 v95, v4
	v_mov_b32_e32 v96, v4
	v_mov_b32_e32 v97, v4
	v_mov_b32_e32 v98, v4
	v_mov_b32_e32 v99, v4
	v_mov_b32_e32 v108, v4
	v_mov_b32_e32 v109, v4
	v_mov_b32_e32 v110, v4
	v_mov_b32_e32 v111, v4
	v_mov_b32_e32 v112, v4
	v_mov_b32_e32 v113, v4
	v_mov_b32_e32 v114, v4
	v_mov_b32_e32 v115, v4
	v_mov_b32_e32 v140, v4
	v_mov_b32_e32 v141, v4
	v_mov_b32_e32 v142, v4
	v_mov_b32_e32 v143, v4
	v_mov_b32_e32 v144, v4
	v_mov_b32_e32 v145, v4
	v_mov_b32_e32 v146, v4
	v_mov_b32_e32 v147, v4
	v_readfirstlane_b32 s101, v156
	s_bfe_u32 s101, s101, 0x10008
.LBB0_559:
	s_add_i32 vcc_lo, s34, 2
	s_add_u32 s35, s42, 0x80
	s_addc_u32 s52, s43, 0
	s_add_i32 s53, 0, 0x10000
	s_cmp_eq_u32 s77, s34
	s_cselect_b32 s57, s51, s52
	s_cselect_b32 s56, s50, s35
	s_cselect_b32 s35, s36, s97
	s_cselect_b32 s34, s37, s49
	s_add_i32 s68, 0, 0x14000
	v_add_u32_e32 v136, s53, v200
	v_add_u32_e32 v186, s68, v200
	ds_read_b128 v[116:119], v136
	ds_read_b128 v[120:123], v136 offset:1024
	ds_read_b128 v[124:127], v136 offset:2048
	ds_read_b128 v[136:139], v136 offset:3072
	ds_read_b128 v[148:151], v186
	ds_read_b128 v[152:155], v186 offset:1024
	ds_read_b128 v[182:185], v186 offset:2048
	ds_read_b128 v[186:189], v186 offset:3072
	v_lshl_add_u64 v[198:199], s[42:43], 0, v[178:179]
	s_add_i32 m0, s59, 0xc000
	ds_read_b128 v[190:193], v202
	ds_read_b128 v[194:197], v202 offset:1024
	ds_read_b128 v[204:207], v202 offset:2048
	ds_read_b128 v[208:211], v202 offset:3072
	ds_read_b128 v[212:215], v202 offset:4096
	ds_read_b128 v[216:219], v202 offset:5120
	ds_read_b128 v[228:231], v202 offset:6144
	ds_read_b128 v[232:235], v202 offset:7168
	global_load_lds_dwordx4 v[198:199], off
	v_lshl_add_u64 v[198:199], s[42:43], 0, v[180:181]
	s_add_i32 m0, s59, 0xe000
	s_nop 0
	global_load_lds_dwordx4 v[198:199], off
	s_waitcnt vmcnt(8)
	s_waitcnt lgkmcnt(0)
	s_cmp_eq_u32 s101, 0
	s_cbranch_scc1 .LnbA_9
	s_barrier
	s_setprio 2
	s_branch .Lnb_17

.Lnb_17:
	v_mfma_f32_16x16x32_bf16 v[144:147], v[116:119], v[190:193], v[144:147]
	v_mfma_f32_16x16x32_bf16 v[144:147], v[120:123], v[194:197], v[144:147]
	v_mfma_f32_16x16x32_bf16 v[140:143], v[124:127], v[190:193], v[140:143]
	v_mfma_f32_16x16x32_bf16 v[140:143], v[136:139], v[194:197], v[140:143]
	v_mfma_f32_16x16x32_bf16 v[108:111], v[124:127], v[204:207], v[108:111]
	v_mfma_f32_16x16x32_bf16 v[108:111], v[136:139], v[208:211], v[108:111]
	v_mfma_f32_16x16x32_bf16 v[112:115], v[116:119], v[204:207], v[112:115]
	v_mfma_f32_16x16x32_bf16 v[112:115], v[120:123], v[208:211], v[112:115]
	v_mfma_f32_16x16x32_bf16 v[96:99], v[116:119], v[212:215], v[96:99]
	v_mfma_f32_16x16x32_bf16 v[96:99], v[120:123], v[216:219], v[96:99]
	v_mfma_f32_16x16x32_bf16 v[92:95], v[124:127], v[212:215], v[92:95]
	v_mfma_f32_16x16x32_bf16 v[92:95], v[136:139], v[216:219], v[92:95]
	v_mfma_f32_16x16x32_bf16 v[76:79], v[124:127], v[228:231], v[76:79]
	v_mfma_f32_16x16x32_bf16 v[76:79], v[136:139], v[232:235], v[76:79]
	v_mfma_f32_16x16x32_bf16 v[80:83], v[116:119], v[228:231], v[80:83]
	v_mfma_f32_16x16x32_bf16 v[80:83], v[120:123], v[232:235], v[80:83]
	v_mfma_f32_16x16x32_bf16 v[132:135], v[148:151], v[190:193], v[132:135]
	v_mfma_f32_16x16x32_bf16 v[132:135], v[152:155], v[194:197], v[132:135]
	v_mfma_f32_16x16x32_bf16 v[128:131], v[182:185], v[190:193], v[128:131]
	v_mfma_f32_16x16x32_bf16 v[128:131], v[186:189], v[194:197], v[128:131]
	v_mfma_f32_16x16x32_bf16 v[100:103], v[182:185], v[204:207], v[100:103]
	v_mfma_f32_16x16x32_bf16 v[100:103], v[186:189], v[208:211], v[100:103]
	v_mfma_f32_16x16x32_bf16 v[104:107], v[148:151], v[204:207], v[104:107]
	v_mfma_f32_16x16x32_bf16 v[104:107], v[152:155], v[208:211], v[104:107]
	v_mfma_f32_16x16x32_bf16 v[88:91], v[148:151], v[212:215], v[88:91]
	v_mfma_f32_16x16x32_bf16 v[88:91], v[152:155], v[216:219], v[88:91]
	v_mfma_f32_16x16x32_bf16 v[84:87], v[182:185], v[212:215], v[84:87]
	v_mfma_f32_16x16x32_bf16 v[84:87], v[186:189], v[216:219], v[84:87]
	v_mfma_f32_16x16x32_bf16 v[68:71], v[182:185], v[228:231], v[68:71]
	v_mfma_f32_16x16x32_bf16 v[68:71], v[186:189], v[232:235], v[68:71]
	v_mfma_f32_16x16x32_bf16 v[72:75], v[148:151], v[228:231], v[72:75]
	v_mfma_f32_16x16x32_bf16 v[72:75], v[152:155], v[232:235], v[72:75]
	s_setprio 0
	s_cmp_lg_u32 s101, 0
	s_cbranch_scc1 .Lnb_18
	s_barrier
.Lnb_18:
	s_add_i32 s52, s53, s58
	v_lshl_add_u64 v[198:199], s[34:35], 0, v[174:175]
	s_mov_b32 m0, s52
	ds_read_b128 v[190:193], v202 offset:16384
	ds_read_b128 v[194:197], v202 offset:17408
	ds_read_b128 v[204:207], v202 offset:18432
	ds_read_b128 v[208:211], v202 offset:19456
	ds_read_b128 v[212:215], v202 offset:20480
	ds_read_b128 v[216:219], v202 offset:21504
	ds_read_b128 v[228:231], v202 offset:22528
	ds_read_b128 v[232:235], v202 offset:23552
	global_load_lds_dwordx4 v[198:199], off
	s_add_i32 m0, s52, 0x2000
	s_add_u32 s52, s34, 0x4000
	v_lshl_add_u64 v[198:199], s[34:35], 0, v[0:1]
	s_addc_u32 s53, s35, 0
	s_add_i32 s68, s68, s58
	global_load_lds_dwordx4 v[198:199], off
	v_lshl_add_u64 v[198:199], s[52:53], 0, v[174:175]
	s_mov_b32 m0, s68
	v_lshl_add_u64 v[236:237], s[56:57], 0, v[172:173]
	global_load_lds_dwordx4 v[198:199], off
	v_lshl_add_u64 v[198:199], s[52:53], 0, v[0:1]
	s_add_i32 m0, s68, 0x2000
	s_nop 0
	global_load_lds_dwordx4 v[198:199], off
	v_lshl_add_u64 v[198:199], s[56:57], 0, v[176:177]
	s_mov_b32 m0, s59
	s_nop 0
	global_load_lds_dwordx4 v[198:199], off
	s_mov_b32 m0, s60
	s_nop 0
	global_load_lds_dwordx4 v[236:237], off
	s_waitcnt vmcnt(8)
	s_waitcnt lgkmcnt(0)
	s_cmp_eq_u32 s101, 0
	s_cbranch_scc1 .LnbA_10
	s_barrier
	s_setprio 2
	s_branch .Lnb_19

.Lnb_19:
	v_mfma_f32_16x16x32_bf16 v[64:67], v[116:119], v[190:193], v[64:67]
	v_mfma_f32_16x16x32_bf16 v[64:67], v[120:123], v[194:197], v[64:67]
	v_mfma_f32_16x16x32_bf16 v[60:63], v[124:127], v[190:193], v[60:63]
	v_mfma_f32_16x16x32_bf16 v[60:63], v[136:139], v[194:197], v[60:63]
	v_mfma_f32_16x16x32_bf16 v[44:47], v[124:127], v[204:207], v[44:47]
	v_mfma_f32_16x16x32_bf16 v[44:47], v[136:139], v[208:211], v[44:47]
	v_mfma_f32_16x16x32_bf16 v[48:51], v[116:119], v[204:207], v[48:51]
	v_mfma_f32_16x16x32_bf16 v[48:51], v[120:123], v[208:211], v[48:51]
	v_mfma_f32_16x16x32_bf16 v[32:35], v[116:119], v[212:215], v[32:35]
	v_mfma_f32_16x16x32_bf16 v[32:35], v[120:123], v[216:219], v[32:35]
	v_mfma_f32_16x16x32_bf16 v[28:31], v[124:127], v[212:215], v[28:31]
	v_mfma_f32_16x16x32_bf16 v[28:31], v[136:139], v[216:219], v[28:31]
	v_mfma_f32_16x16x32_bf16 v[12:15], v[124:127], v[228:231], v[12:15]
	v_mfma_f32_16x16x32_bf16 v[12:15], v[136:139], v[232:235], v[12:15]
	v_mfma_f32_16x16x32_bf16 v[16:19], v[116:119], v[228:231], v[16:19]
	v_mfma_f32_16x16x32_bf16 v[16:19], v[120:123], v[232:235], v[16:19]
	v_mfma_f32_16x16x32_bf16 v[56:59], v[148:151], v[190:193], v[56:59]
	v_mfma_f32_16x16x32_bf16 v[56:59], v[152:155], v[194:197], v[56:59]
	v_mfma_f32_16x16x32_bf16 v[52:55], v[182:185], v[190:193], v[52:55]
	v_mfma_f32_16x16x32_bf16 v[52:55], v[186:189], v[194:197], v[52:55]
	v_mfma_f32_16x16x32_bf16 v[36:39], v[182:185], v[204:207], v[36:39]
	v_mfma_f32_16x16x32_bf16 v[36:39], v[186:189], v[208:211], v[36:39]
	v_mfma_f32_16x16x32_bf16 v[40:43], v[148:151], v[204:207], v[40:43]
	v_mfma_f32_16x16x32_bf16 v[40:43], v[152:155], v[208:211], v[40:43]
	v_mfma_f32_16x16x32_bf16 v[24:27], v[148:151], v[212:215], v[24:27]
	v_mfma_f32_16x16x32_bf16 v[24:27], v[152:155], v[216:219], v[24:27]
	v_mfma_f32_16x16x32_bf16 v[20:23], v[182:185], v[212:215], v[20:23]
	v_mfma_f32_16x16x32_bf16 v[20:23], v[186:189], v[216:219], v[20:23]
	v_mfma_f32_16x16x32_bf16 v[4:7], v[182:185], v[228:231], v[4:7]
	v_mfma_f32_16x16x32_bf16 v[4:7], v[186:189], v[232:235], v[4:7]
	v_mfma_f32_16x16x32_bf16 v[8:11], v[148:151], v[228:231], v[8:11]
	v_mfma_f32_16x16x32_bf16 v[8:11], v[152:155], v[232:235], v[8:11]
	s_setprio 0
	s_cmp_lg_u32 s101, 0
	s_cbranch_scc1 .Lnb_20
	s_barrier
.Lnb_20:
	s_add_i32 s68, 0, 0x18000
	s_add_i32 vcc_hi, 0, 0x1c000
	v_add_u32_e32 v136, s68, v200
	v_add_u32_e32 v186, vcc_hi, v200
	ds_read_b128 v[116:119], v136
	ds_read_b128 v[120:123], v136 offset:1024
	ds_read_b128 v[124:127], v136 offset:2048
	ds_read_b128 v[136:139], v136 offset:3072
	ds_read_b128 v[148:151], v186
	ds_read_b128 v[152:155], v186 offset:1024
	ds_read_b128 v[182:185], v186 offset:2048
	ds_read_b128 v[186:189], v186 offset:3072
	s_add_u32 s52, s56, s26
	s_addc_u32 s53, s57, 0
	s_mov_b32 m0, s61
	v_lshl_add_u64 v[238:239], s[52:53], 0, v[176:177]
	ds_read_b128 v[190:193], v202 offset:32768
	ds_read_b128 v[194:197], v202 offset:33792
	ds_read_b128 v[204:207], v202 offset:34816
	ds_read_b128 v[208:211], v202 offset:35840
	ds_read_b128 v[212:215], v202 offset:36864
	ds_read_b128 v[216:219], v202 offset:37888
	ds_read_b128 v[228:231], v202 offset:38912
	ds_read_b128 v[232:235], v202 offset:39936
	global_load_lds_dwordx4 v[238:239], off
	v_lshl_add_u64 v[238:239], s[52:53], 0, v[172:173]
	s_mov_b32 m0, s62
	s_nop 0
	global_load_lds_dwordx4 v[238:239], off
	s_waitcnt vmcnt(8)
	s_waitcnt lgkmcnt(0)
	s_cmp_eq_u32 s101, 0
	s_cbranch_scc1 .LnbA_11
	s_barrier
	s_setprio 2
	s_branch .Lnb_21

.Lnb_22:
	s_add_u32 s52, s34, 0x40000
	s_addc_u32 s53, s35, 0
	s_add_i32 s56, s68, s58
	v_lshl_add_u64 v[238:239], s[52:53], 0, v[174:175]
	s_mov_b32 m0, s56
	ds_read_b128 v[190:193], v202 offset:49152
	ds_read_b128 v[194:197], v202 offset:50176
	ds_read_b128 v[204:207], v202 offset:51200
	ds_read_b128 v[208:211], v202 offset:52224
	ds_read_b128 v[212:215], v202 offset:53248
	ds_read_b128 v[216:219], v202 offset:54272
	ds_read_b128 v[228:231], v202 offset:55296
	ds_read_b128 v[232:235], v202 offset:56320
	global_load_lds_dwordx4 v[238:239], off
	s_add_i32 m0, s56, 0x2000
	s_add_u32 s34, s34, 0x44000
	v_lshl_add_u64 v[238:239], s[52:53], 0, v[0:1]
	s_addc_u32 s35, s35, 0
	s_add_i32 s52, vcc_hi, s58
	global_load_lds_dwordx4 v[238:239], off
	v_lshl_add_u64 v[238:239], s[34:35], 0, v[174:175]
	s_mov_b32 m0, s52
	v_lshl_add_u64 v[198:199], v[198:199], 0, s[14:15]
	global_load_lds_dwordx4 v[238:239], off
	v_lshl_add_u64 v[238:239], s[34:35], 0, v[0:1]
	s_add_i32 m0, s52, 0x2000
	s_nop 0
	global_load_lds_dwordx4 v[238:239], off
	s_mov_b32 m0, s71
	s_nop 0
	global_load_lds_dwordx4 v[198:199], off
	v_lshl_add_u64 v[198:199], v[236:237], 0, s[14:15]
	s_mov_b32 m0, s76
	s_nop 0
	global_load_lds_dwordx4 v[198:199], off
	s_waitcnt vmcnt(8)
	s_waitcnt lgkmcnt(0)
	s_cmp_eq_u32 s101, 0
	s_cbranch_scc1 .LnbA_12
	s_barrier
	s_setprio 2
	s_branch .Lnb_23

.Lnb_24:
	s_add_u32 s49, s49, 0x80000
	s_addc_u32 s97, s97, 0
	s_add_u32 s42, s42, 0x100
	s_addc_u32 s43, s43, 0
	s_cmp_ge_u32 vcc_lo, s69
	s_mov_b32 s34, vcc_lo
	s_cbranch_scc0 .LBB0_559
	s_and_b64 vcc, exec, s[46:47]
	s_nop 0
	s_barrier

.LBB0_578:
	s_or_b64 exec, exec, s[34:35]
	s_and_b64 vcc, exec, s[40:41]
	s_mov_b64 s[34:35], -1
	s_cbranch_vccnz .LBB0_549
	s_andn2_b64 vcc, exec, s[28:29]
	s_cbranch_vccnz .LBB0_548
	s_nop 0
	s_branch .LBB0_548
